# hoisted serialized global loads (rowscale prologues, sgu stats/LN/weight loads), LDS ds ops for attn_d done-flags, norm next-token prefetch
# speedup vs baseline: 1.0623x; 1.0157x over previous
; DI void phase_norm(const float* xin, u16* hb) {
;     ...
;   for (int t = gw; t < T_TOK; t += nw) {
;     const float* r = xin + (size_t)t * DM;
;     float4 v[4];
;     float ss = 0.f;
; #pragma unroll
;     for (int i = 0; i < 4; ++i) {
;       v[i] = *(const float4*)(r + i * 256 + lane * 4);
;       ss += v[i].x * v[i].x + v[i].y * v[i].y + v[i].z * v[i].z + v[i].w * v[i].w;
;     }
; #pragma unroll
;     for (int o = 32; o > 0; o >>= 1) ss += __shfl_xor(ss, o);
;     const float rs = rsqrtf(ss * (1.f / DM) + EPS);
; #pragma unroll
;     for (int i = 0; i < 4; ++i) {
;       u32x2 o = {pack2(v[i].x * rs, v[i].y * rs), pack2(v[i].z * rs, v[i].w * rs)};
;       *(u32x2*)(hb + (size_t)t * DM + i * 256 + lane * 4) = o;
;     }
;   }
.LBB0_126:
	global_load_dwordx4 v[40:43], v[4:5], off
	global_load_dwordx4 v[44:47], v[4:5], off offset:1024
	global_load_dwordx4 v[48:51], v[4:5], off offset:2048
	global_load_dwordx4 v[52:55], v[4:5], off offset:3072
	s_waitcnt vmcnt(0)
.Lnrm_a:
	v_mov_b32_e32 v12, v40
	v_mov_b32_e32 v13, v41
	v_mov_b32_e32 v14, v42
	v_mov_b32_e32 v15, v43
	v_mov_b32_e32 v16, v44
	v_mov_b32_e32 v17, v45
	v_mov_b32_e32 v18, v46
	v_mov_b32_e32 v19, v47
	v_add_u32_e32 v0, s84, v0
	v_mov_b32_e32 v26, v13
	v_mov_b32_e32 v27, v17
	v_mov_b32_e32 v24, v12
	v_mov_b32_e32 v25, v16
	v_pk_mul_f32 v[26:27], v[26:27], v[26:27]
	v_mov_b32_e32 v20, v14
	v_mov_b32_e32 v21, v18
	v_pk_fma_f32 v[24:25], v[24:25], v[24:25], v[26:27]
	v_mov_b32_e32 v22, v15
	v_mov_b32_e32 v23, v19
	v_pk_fma_f32 v[20:21], v[20:21], v[20:21], v[24:25]
	s_nop 0
	v_pk_fma_f32 v[28:29], v[22:23], v[22:23], v[20:21]
	v_mov_b32_e32 v20, v48
	v_mov_b32_e32 v21, v49
	v_mov_b32_e32 v22, v50
	v_mov_b32_e32 v23, v51
	v_mov_b32_e32 v24, v52
	v_mov_b32_e32 v25, v53
	v_mov_b32_e32 v26, v54
	v_mov_b32_e32 v27, v55
	v_add_f32_e32 v1, v28, v29
	v_lshl_add_u64 v[4:5], v[4:5], 0, s[14:15]
	v_cmp_lt_i32_e32 vcc, s60, v0
	s_cbranch_vccnz .Lnrm_skip_a
	global_load_dwordx4 v[40:43], v[4:5], off
	global_load_dwordx4 v[44:47], v[4:5], off offset:1024
	global_load_dwordx4 v[48:51], v[4:5], off offset:2048
	global_load_dwordx4 v[52:55], v[4:5], off offset:3072
.Lnrm_skip_a:
	v_mov_b32_e32 v36, v21
	v_mov_b32_e32 v37, v25
	v_mov_b32_e32 v34, v20
	v_mov_b32_e32 v35, v24
	v_pk_mul_f32 v[36:37], v[36:37], v[36:37]
	v_mov_b32_e32 v30, v22
	v_mov_b32_e32 v31, v26
	v_pk_fma_f32 v[34:35], v[34:35], v[34:35], v[36:37]
	v_mov_b32_e32 v32, v23
	v_mov_b32_e32 v33, v27
	v_pk_fma_f32 v[30:31], v[30:31], v[30:31], v[34:35]
	s_nop 0
	v_pk_fma_f32 v[30:31], v[32:33], v[32:33], v[30:31]
	s_nop 0
	v_add_f32_e32 v1, v1, v30
	v_add_f32_e32 v1, v1, v31
	ds_bpermute_b32 v28, v6, v1
	s_waitcnt lgkmcnt(0)
	v_add_f32_e32 v1, v1, v28
	ds_bpermute_b32 v28, v7, v1
	s_waitcnt lgkmcnt(0)
	v_add_f32_e32 v1, v1, v28
	ds_bpermute_b32 v28, v8, v1
	s_waitcnt lgkmcnt(0)
	v_add_f32_e32 v1, v1, v28
	ds_bpermute_b32 v28, v9, v1
	s_waitcnt lgkmcnt(0)
	v_add_f32_e32 v1, v1, v28
	ds_bpermute_b32 v28, v10, v1
	s_waitcnt lgkmcnt(0)
	v_add_f32_e32 v1, v1, v28
	ds_bpermute_b32 v28, v11, v1
	s_waitcnt lgkmcnt(0)
	v_add_f32_e32 v1, v1, v28
	v_fmamk_f32 v1, v1, 0x3a800000, v134
	v_cmp_gt_f32_e32 vcc, s33, v1
	v_mul_f32_e32 v28, 0x4b800000, v1
	s_nop 0
	v_cndmask_b32_e32 v1, v1, v28, vcc
	v_rsq_f32_e32 v1, v1
	s_nop 0
	v_mul_f32_e32 v28, 0x45800000, v1
	v_cndmask_b32_e32 v28, v1, v28, vcc
	v_pk_mul_f32 v[12:13], v[12:13], v[28:29] op_sel_hi:[1,0]
	v_pk_mul_f32 v[14:15], v[14:15], v[28:29] op_sel_hi:[1,0]
	v_cvt_pk_bf16_f32 v12, v12, v13
	v_cvt_pk_bf16_f32 v13, v14, v15
	global_store_dwordx2 v[2:3], v[12:13], off
	v_pk_mul_f32 v[12:13], v[16:17], v[28:29] op_sel_hi:[1,0]
	v_pk_mul_f32 v[14:15], v[18:19], v[28:29] op_sel_hi:[1,0]
	v_cvt_pk_bf16_f32 v12, v12, v13
	v_cvt_pk_bf16_f32 v13, v14, v15
	global_store_dwordx2 v[2:3], v[12:13], off offset:512
	v_pk_mul_f32 v[12:13], v[20:21], v[28:29] op_sel_hi:[1,0]
	v_pk_mul_f32 v[14:15], v[22:23], v[28:29] op_sel_hi:[1,0]
	v_cvt_pk_bf16_f32 v12, v12, v13
	v_cvt_pk_bf16_f32 v13, v14, v15
	global_store_dwordx2 v[2:3], v[12:13], off offset:1024
	v_pk_mul_f32 v[12:13], v[24:25], v[28:29] op_sel_hi:[1,0]
	v_pk_mul_f32 v[14:15], v[26:27], v[28:29] op_sel_hi:[1,0]
	v_cvt_pk_bf16_f32 v12, v12, v13
	v_cvt_pk_bf16_f32 v13, v14, v15
	v_cmp_lt_i32_e32 vcc, s60, v0
	global_store_dwordx2 v[2:3], v[12:13], off offset:1536
	v_lshl_add_u64 v[2:3], v[2:3], 0, s[12:13]
	s_or_b64 s[4:5], vcc, s[4:5]
	s_andn2_b64 exec, exec, s[4:5]
	s_waitcnt vmcnt(4)
	s_cbranch_execnz .Lnrm_a

;     ...
;       if (lane == 0) sdone[cur * 8 + wid] = done;
;       asm volatile("s_waitcnt vmcnt(0)" ::: "memory");
;       __syncthreads();
;       int alld = 1;
; #pragma unroll
;       for (int w = 0; w < 8; ++w) alld &= sdone[cur * 8 + w];
;       if (alld || !more) break;
.LBB0_399:
	s_lshl_b32 s12, s71, 5
	s_and_saveexec_b64 s[10:11], s[6:7]
	s_cbranch_execz .LBB0_401
	s_add_i32 s13, s56, s12
	v_mov_b32_e32 v50, s13
	ds_write_b32 v50, v48
.LBB0_401:
	s_or_b64 exec, exec, s[10:11]
	s_or_b32 s13, s12, 0x10000
	v_mov_b32_e32 v50, s13
	s_waitcnt vmcnt(0) lgkmcnt(0)
	s_barrier
	ds_read_b128 v[52:55], v50
	ds_read_b128 v[56:59], v50 offset:16
	s_mov_b64 s[10:11], -1
	s_waitcnt lgkmcnt(0)
	v_bitop3_b32 v49, v52, v53, v54 bitop3:0x80
	v_bitop3_b32 v49, v49, v55, v56 bitop3:0x80
	v_bitop3_b32 v49, v49, v57, v58 bitop3:0x80
	v_bitop3_b32 v49, v49, 1, v59 bitop3:0x80
	v_cmp_eq_u32_e32 vcc, 0, v49
	s_and_b64 s[14:15], s[84:85], vcc
	s_and_saveexec_b64 s[12:13], s[14:15]
	s_cbranch_execz .LBB0_369
	s_add_i32 s61, s61, 1
	s_sub_i32 s60, s60, 64
	v_add_u32_e32 v74, 0xffff0000, v74
	v_add_u32_e32 v76, 0xffff0000, v76
	s_xor_b64 s[10:11], exec, -1
	s_branch .LBB0_369

; DI float bflo(unsigned v) { return __uint_as_float(v << 16); }
; DI float bfhi(unsigned v) { return __uint_as_float(v & 0xffff0000u); }
; DI int tid_() { int t = threadIdx.x; asm volatile("" : "+v"(t)); return t; }
; DI void rowscale_prologue(const u16* Ab, int lda, int K, float* rs) {
;   const int tid = tid_(), row = tid >> 1, half = tid & 1;
;   const u16* p = Ab + (long)row * lda + half * (K >> 1);
;   float ss = 0.f;
;   for (int i = 0; i < (K >> 4); ++i) {
;     i32x4 v = *(const i32x4*)(p + i * 8);
; #pragma unroll
;     for (int e = 0; e < 4; ++e) {
;       float a = bflo((unsigned)v[e]), b = bfhi((unsigned)v[e]);
;       ss += a * a + b * b;
;     }
;   }
;   ss += __shfl_xor(ss, 1);
;   if (half == 0) rs[row] = rsqrtf(ss / (float)K + EPS);
.LBB0_406:
	s_ashr_i32 s0, s24, 31
	s_lshr_b32 s0, s0, 29
	s_add_i32 s0, s24, s0
	s_ashr_i32 s1, s0, 3
	s_and_b32 s0, s0, -8
	s_sub_i32 s0, s24, s0
	s_lshr_b32 s4, s0, 31
	s_or_b32 s4, s4, 64
	s_mul_i32 s0, s4, s0
	s_add_i32 s0, s0, s1
	s_ashr_i32 s1, s0, 31
	s_lshr_b32 s1, s1, 27
	s_add_i32 s1, s0, s1
	s_ashr_i32 s4, s1, 5
	s_lshl_b32 s26, s4, 3
	s_sub_i32 s4, 0x80, s26
	s_min_u32 s4, s4, 8
	s_andn2_b32 s1, s1, 31
	s_sub_i32 s5, s0, s1
	v_cvt_f32_ubyte0_e32 v1, s4
	v_cvt_f32_i32_e32 v0, s5
	v_rcp_iflag_f32_e32 v2, v1
	s_ashr_i32 s0, s5, 30
	s_or_b32 s18, s0, 1
	v_mul_f32_e32 v2, v0, v2
	v_trunc_f32_e32 v2, v2
	v_fma_f32 v0, -v2, v1, v0
	v_cvt_i32_f32_e32 v2, v2
	v_cmp_ge_f32_e64 s[0:1], |v0|, v1
	s_and_b64 s[0:1], s[0:1], exec
	s_cselect_b32 s0, s18, 0
	v_readfirstlane_b32 s27, v2
	s_add_i32 s27, s27, s0
	s_mul_i32 s0, s27, s4
	s_sub_i32 s0, s5, s0
	s_sext_i32_i8 s0, s0
	s_add_i32 s26, s26, s0
	s_lshl_b32 s25, s26, 8
	s_mul_i32 s0, s26, 0x38000
	s_mul_hi_i32 s1, s25, 0x380
	s_add_u32 s0, s10, s0
	v_mov_b32_e32 v0, v135
	s_addc_u32 s1, s11, s1
	s_nop 0
	v_ashrrev_i32_e32 v4, 1, v0
	v_and_b32_e32 v5, 1, v0
	v_mov_b64_e32 v[0:1], s[0:1]
	v_mad_i64_i32 v[0:1], s[4:5], v4, s69, v[0:1]
	v_lshlrev_b32_e32 v132, 7, v5
	v_lshl_add_u64 v[0:1], v[0:1], 0, v[132:133]
	global_load_dwordx4 v[16:19], v[0:1], off offset:512
	global_load_dwordx4 v[20:23], v[0:1], off offset:528
	global_load_dwordx4 v[24:27], v[0:1], off offset:544
	global_load_dwordx4 v[28:31], v[0:1], off offset:560
	global_load_dwordx4 v[32:35], v[0:1], off offset:576
	global_load_dwordx4 v[36:39], v[0:1], off offset:592
	global_load_dwordx4 v[40:43], v[0:1], off offset:608
	global_load_dwordx4 v[44:47], v[0:1], off offset:624
	s_waitcnt vmcnt(7) lgkmcnt(0)
	v_and_b32_e32 v3, 0xffff0000, v16
	v_lshlrev_b32_e32 v2, 16, v16
	v_mul_f32_e32 v3, v3, v3
	v_and_b32_e32 v6, 0xffff0000, v17
	v_fmac_f32_e32 v3, v2, v2
	v_lshlrev_b32_e32 v2, 16, v17
	v_mul_f32_e32 v6, v6, v6
	v_fmac_f32_e32 v6, v2, v2
	v_add_f32_e32 v2, v6, v3
	v_and_b32_e32 v6, 0xffff0000, v18
	v_lshlrev_b32_e32 v3, 16, v18
	v_mul_f32_e32 v6, v6, v6
	v_fmac_f32_e32 v6, v3, v3
	v_add_f32_e32 v2, v6, v2
	v_and_b32_e32 v6, 0xffff0000, v19
	v_lshlrev_b32_e32 v3, 16, v19
	v_mul_f32_e32 v6, v6, v6
	v_fmac_f32_e32 v6, v3, v3
	v_add_f32_e32 v2, v6, v2
	s_waitcnt vmcnt(6) lgkmcnt(0)
	v_lshlrev_b32_e32 v3, 16, v20
	v_and_b32_e32 v6, 0xffff0000, v20
	v_mul_f32_e32 v6, v6, v6
	v_fmac_f32_e32 v6, v3, v3
	v_add_f32_e32 v2, v6, v2
	v_and_b32_e32 v6, 0xffff0000, v21
	v_lshlrev_b32_e32 v3, 16, v21
	v_mul_f32_e32 v6, v6, v6
	v_fmac_f32_e32 v6, v3, v3
	v_add_f32_e32 v2, v6, v2
	v_and_b32_e32 v6, 0xffff0000, v22
	v_lshlrev_b32_e32 v3, 16, v22
	v_mul_f32_e32 v6, v6, v6
	v_fmac_f32_e32 v6, v3, v3
	v_add_f32_e32 v2, v6, v2
	v_and_b32_e32 v6, 0xffff0000, v23
	v_lshlrev_b32_e32 v3, 16, v23
	v_mul_f32_e32 v6, v6, v6
	v_fmac_f32_e32 v6, v3, v3
	v_add_f32_e32 v2, v6, v2
	s_waitcnt vmcnt(5) lgkmcnt(0)
	v_lshlrev_b32_e32 v3, 16, v24
	v_and_b32_e32 v6, 0xffff0000, v24
	v_mul_f32_e32 v6, v6, v6
	v_fmac_f32_e32 v6, v3, v3
	v_add_f32_e32 v2, v6, v2
	v_and_b32_e32 v6, 0xffff0000, v25
	v_lshlrev_b32_e32 v3, 16, v25
	v_mul_f32_e32 v6, v6, v6
	v_fmac_f32_e32 v6, v3, v3
	v_add_f32_e32 v2, v6, v2
	v_and_b32_e32 v6, 0xffff0000, v26
	v_lshlrev_b32_e32 v3, 16, v26
	v_mul_f32_e32 v6, v6, v6
	v_fmac_f32_e32 v6, v3, v3
	v_add_f32_e32 v2, v6, v2
	v_and_b32_e32 v6, 0xffff0000, v27
	v_lshlrev_b32_e32 v3, 16, v27
	v_mul_f32_e32 v6, v6, v6
	v_fmac_f32_e32 v6, v3, v3
	v_add_f32_e32 v2, v6, v2
	s_waitcnt vmcnt(4) lgkmcnt(0)
	v_lshlrev_b32_e32 v3, 16, v28
	v_and_b32_e32 v6, 0xffff0000, v28
	v_mul_f32_e32 v6, v6, v6
	v_fmac_f32_e32 v6, v3, v3
	v_add_f32_e32 v2, v6, v2
	v_and_b32_e32 v6, 0xffff0000, v29
	v_lshlrev_b32_e32 v3, 16, v29
	v_mul_f32_e32 v6, v6, v6
	v_fmac_f32_e32 v6, v3, v3
	v_add_f32_e32 v2, v6, v2
	v_and_b32_e32 v6, 0xffff0000, v30
	v_lshlrev_b32_e32 v3, 16, v30
	v_mul_f32_e32 v6, v6, v6
	v_fmac_f32_e32 v6, v3, v3
	v_add_f32_e32 v2, v6, v2
	v_and_b32_e32 v6, 0xffff0000, v31
	v_lshlrev_b32_e32 v3, 16, v31
	v_mul_f32_e32 v6, v6, v6
	v_fmac_f32_e32 v6, v3, v3
	v_add_f32_e32 v2, v6, v2
	s_waitcnt vmcnt(3) lgkmcnt(0)
	v_lshlrev_b32_e32 v3, 16, v32
	v_and_b32_e32 v6, 0xffff0000, v32
	v_mul_f32_e32 v6, v6, v6
	v_fmac_f32_e32 v6, v3, v3
	v_add_f32_e32 v2, v6, v2
	v_and_b32_e32 v6, 0xffff0000, v33
	v_lshlrev_b32_e32 v3, 16, v33
	v_mul_f32_e32 v6, v6, v6
	v_fmac_f32_e32 v6, v3, v3
	v_add_f32_e32 v2, v6, v2
	v_and_b32_e32 v6, 0xffff0000, v34
	v_lshlrev_b32_e32 v3, 16, v34
	v_mul_f32_e32 v6, v6, v6
	v_fmac_f32_e32 v6, v3, v3
	v_add_f32_e32 v2, v6, v2
	v_and_b32_e32 v6, 0xffff0000, v35
	v_lshlrev_b32_e32 v3, 16, v35
	v_mul_f32_e32 v6, v6, v6
	v_fmac_f32_e32 v6, v3, v3
	v_add_f32_e32 v2, v6, v2
	s_waitcnt vmcnt(2) lgkmcnt(0)
	v_lshlrev_b32_e32 v3, 16, v36
	v_and_b32_e32 v6, 0xffff0000, v36
	v_mul_f32_e32 v6, v6, v6
	v_fmac_f32_e32 v6, v3, v3
	v_add_f32_e32 v2, v6, v2
	v_and_b32_e32 v6, 0xffff0000, v37
	v_lshlrev_b32_e32 v3, 16, v37
	v_mul_f32_e32 v6, v6, v6
	v_fmac_f32_e32 v6, v3, v3
	v_add_f32_e32 v2, v6, v2
	v_and_b32_e32 v6, 0xffff0000, v38
	v_lshlrev_b32_e32 v3, 16, v38
	v_mul_f32_e32 v6, v6, v6
	v_fmac_f32_e32 v6, v3, v3
	v_add_f32_e32 v2, v6, v2
	v_and_b32_e32 v6, 0xffff0000, v39
	v_lshlrev_b32_e32 v3, 16, v39
	v_mul_f32_e32 v6, v6, v6
	v_fmac_f32_e32 v6, v3, v3
	v_add_f32_e32 v2, v6, v2
	s_waitcnt vmcnt(1) lgkmcnt(0)
	v_lshlrev_b32_e32 v3, 16, v40
	v_and_b32_e32 v6, 0xffff0000, v40
	v_mul_f32_e32 v6, v6, v6
	v_fmac_f32_e32 v6, v3, v3
	v_add_f32_e32 v2, v6, v2
	v_and_b32_e32 v6, 0xffff0000, v41
	v_lshlrev_b32_e32 v3, 16, v41
	v_mul_f32_e32 v6, v6, v6
	v_fmac_f32_e32 v6, v3, v3
	v_add_f32_e32 v2, v6, v2
	v_and_b32_e32 v6, 0xffff0000, v42
	v_lshlrev_b32_e32 v3, 16, v42
	v_mul_f32_e32 v6, v6, v6
	v_fmac_f32_e32 v6, v3, v3
	v_add_f32_e32 v2, v6, v2
	v_and_b32_e32 v6, 0xffff0000, v43
	v_lshlrev_b32_e32 v3, 16, v43
	v_mul_f32_e32 v6, v6, v6
	v_fmac_f32_e32 v6, v3, v3
	v_add_f32_e32 v6, v6, v2
	s_waitcnt vmcnt(0) lgkmcnt(0)
	v_lshlrev_b32_e32 v7, 16, v44
	v_and_b32_e32 v0, 0xffff0000, v44
	v_mul_f32_e32 v0, v0, v0
	v_fmac_f32_e32 v0, v7, v7
	v_add_f32_e32 v0, v0, v6
	v_lshlrev_b32_e32 v6, 16, v45
	v_and_b32_e32 v1, 0xffff0000, v45
	v_mul_f32_e32 v1, v1, v1
	v_fmac_f32_e32 v1, v6, v6
	v_add_f32_e32 v0, v1, v0
	v_lshlrev_b32_e32 v1, 16, v46
	v_and_b32_e32 v2, 0xffff0000, v46
	v_mul_f32_e32 v2, v2, v2
	v_fmac_f32_e32 v2, v1, v1
	v_add_f32_e32 v0, v2, v0
	v_and_b32_e32 v2, 0xffff0000, v47
	v_lshlrev_b32_e32 v1, 16, v47
	v_mul_f32_e32 v2, v2, v2
	v_fmac_f32_e32 v2, v1, v1
	v_add_f32_e32 v0, v2, v0
	v_mov_b32_e32 v3, v47
	v_mov_b32_e32 v8, v42
	v_mov_b32_e32 v9, v43
	v_and_b32_e32 v2, 64, v204
	v_xor_b32_e32 v1, 1, v204
	v_add_u32_e32 v132, 64, v2
	v_cmp_lt_i32_e32 vcc, v1, v132
	s_nop 1
	v_cndmask_b32_e32 v1, v204, v1, vcc
	v_lshlrev_b32_e32 v162, 2, v1
	ds_bpermute_b32 v1, v162, v0
	v_cmp_eq_u32_e32 vcc, 0, v5
	s_and_saveexec_b64 s[4:5], vcc
	s_cbranch_execz .LBB0_408
; DI void rowscale_prologue(const u16* Ab, int lda, int K, float* rs) {
;     ...
;   ss += __shfl_xor(ss, 1);
;   if (half == 0) rs[row] = rsqrtf(ss / (float)K + EPS);
	s_waitcnt lgkmcnt(0)
	v_add_f32_e32 v0, v0, v1
	v_fmamk_f32 v0, v0, 0x3c000000, v134
	v_mul_f32_e32 v1, 0x4b800000, v0
	v_cmp_gt_f32_e32 vcc, s33, v0
	s_nop 1
	v_cndmask_b32_e32 v0, v0, v1, vcc
	v_rsq_f32_e32 v0, v0
	s_nop 0
	v_mul_f32_e32 v1, 0x45800000, v0
	v_cndmask_b32_e32 v0, v0, v1, vcc
	v_lshl_add_u32 v1, v4, 2, v210
	ds_write_b32 v1, v0

; DI float bflo(unsigned v) { return __uint_as_float(v << 16); }
; DI float bfhi(unsigned v) { return __uint_as_float(v & 0xffff0000u); }
; DI int tid_() { int t = threadIdx.x; asm volatile("" : "+v"(t)); return t; }
; DI void rowscale_prologue(const u16* Ab, int lda, int K, float* rs) {
;   const int tid = tid_(), row = tid >> 1, half = tid & 1;
;   const u16* p = Ab + (long)row * lda + half * (K >> 1);
;   float ss = 0.f;
;   for (int i = 0; i < (K >> 4); ++i) {
;     i32x4 v = *(const i32x4*)(p + i * 8);
; #pragma unroll
;     for (int e = 0; e < 4; ++e) {
;       float a = bflo((unsigned)v[e]), b = bfhi((unsigned)v[e]);
;       ss += a * a + b * b;
;     }
;   }
;   ss += __shfl_xor(ss, 1);
;   if (half == 0) rs[row] = rsqrtf(ss / (float)K + EPS);
;   __syncthreads();
; }
.LBB0_548:
	v_lshl_add_u64 v[2:3], v[0:1], 0, s[0:1]
	v_add_co_u32_e32 v2, vcc, 0xf000000, v2
	s_add_u32 s0, s0, 64
	s_nop 0
	v_addc_co_u32_e32 v3, vcc, 0, v3, vcc
	global_load_dwordx4 v[16:19], v[2:3], off
	global_load_dwordx4 v[20:23], v[2:3], off offset:16
	global_load_dwordx4 v[24:27], v[2:3], off offset:32
	global_load_dwordx4 v[28:31], v[2:3], off offset:48
	s_addc_u32 s1, s1, 0
	s_cmpk_eq_i32 s0, 0x100
	s_waitcnt vmcnt(3) lgkmcnt(0)
	v_lshlrev_b32_e32 v12, 16, v16
	v_and_b32_e32 v13, 0xffff0000, v16
	v_pk_mul_f32 v[12:13], v[12:13], v[12:13]
	s_nop 0
	v_add_f32_e32 v7, v12, v13
	v_and_b32_e32 v13, 0xffff0000, v18
	v_and_b32_e32 v12, 0xffff0000, v17
	v_add_f32_e32 v14, v6, v7
	v_lshlrev_b32_e32 v7, 16, v18
	v_lshlrev_b32_e32 v6, 16, v17
	v_pk_mul_f32 v[8:9], v[12:13], v[12:13]
	s_nop 0
	v_pk_fma_f32 v[6:7], v[6:7], v[6:7], v[8:9]
	s_nop 0
	v_add_f32_e32 v6, v6, v14
	v_add_f32_e32 v8, v7, v6
	v_lshlrev_b32_e32 v6, 16, v19
	v_and_b32_e32 v7, 0xffff0000, v19
	v_pk_mul_f32 v[6:7], v[6:7], v[6:7]
	s_nop 0
	v_add_f32_e32 v6, v6, v7
	v_add_f32_e32 v12, v6, v8
	s_waitcnt vmcnt(2) lgkmcnt(0)
	v_lshlrev_b32_e32 v10, 16, v20
	v_and_b32_e32 v11, 0xffff0000, v20
	v_pk_mul_f32 v[10:11], v[10:11], v[10:11]
	v_and_b32_e32 v13, 0xffff0000, v22
	v_add_f32_e32 v6, v10, v11
	v_add_f32_e32 v14, v12, v6
	v_and_b32_e32 v12, 0xffff0000, v21
	v_lshlrev_b32_e32 v11, 16, v22
	v_lshlrev_b32_e32 v10, 16, v21
	v_pk_mul_f32 v[6:7], v[12:13], v[12:13]
	s_nop 0
	v_pk_fma_f32 v[6:7], v[10:11], v[10:11], v[6:7]
	s_nop 0
	v_add_f32_e32 v6, v6, v14
	v_add_f32_e32 v8, v7, v6
	v_lshlrev_b32_e32 v6, 16, v23
	v_and_b32_e32 v7, 0xffff0000, v23
	v_pk_mul_f32 v[6:7], v[6:7], v[6:7]
	s_nop 0
	v_add_f32_e32 v6, v6, v7
	v_add_f32_e32 v12, v6, v8
	s_waitcnt vmcnt(1) lgkmcnt(0)
	v_lshlrev_b32_e32 v10, 16, v24
	v_and_b32_e32 v11, 0xffff0000, v24
	v_pk_mul_f32 v[10:11], v[10:11], v[10:11]
	v_and_b32_e32 v13, 0xffff0000, v26
	v_add_f32_e32 v6, v10, v11
	v_add_f32_e32 v14, v12, v6
	v_and_b32_e32 v12, 0xffff0000, v25
	v_lshlrev_b32_e32 v11, 16, v26
	v_lshlrev_b32_e32 v10, 16, v25
	v_pk_mul_f32 v[6:7], v[12:13], v[12:13]
	s_nop 0
	v_pk_fma_f32 v[6:7], v[10:11], v[10:11], v[6:7]
	s_nop 0
	v_add_f32_e32 v6, v6, v14
	v_add_f32_e32 v8, v7, v6
	v_lshlrev_b32_e32 v6, 16, v27
	v_and_b32_e32 v7, 0xffff0000, v27
	v_pk_mul_f32 v[6:7], v[6:7], v[6:7]
	s_nop 0
	v_add_f32_e32 v6, v6, v7
	v_add_f32_e32 v10, v6, v8
	s_waitcnt vmcnt(0) lgkmcnt(0)
	v_lshlrev_b32_e32 v2, 16, v28
	v_and_b32_e32 v3, 0xffff0000, v28
	v_pk_mul_f32 v[2:3], v[2:3], v[2:3]
	v_and_b32_e32 v11, 0xffff0000, v30
	v_add_f32_e32 v2, v2, v3
	v_add_f32_e32 v12, v10, v2
	v_and_b32_e32 v10, 0xffff0000, v29
	v_lshlrev_b32_e32 v3, 16, v30
	v_lshlrev_b32_e32 v2, 16, v29
	v_pk_mul_f32 v[6:7], v[10:11], v[10:11]
	s_nop 0
	v_pk_fma_f32 v[2:3], v[2:3], v[2:3], v[6:7]
	s_nop 0
	v_add_f32_e32 v2, v2, v12
	v_add_f32_e32 v6, v3, v2
	v_lshlrev_b32_e32 v2, 16, v31
	v_and_b32_e32 v3, 0xffff0000, v31
	v_pk_mul_f32 v[2:3], v[2:3], v[2:3]
	s_nop 0
	v_add_f32_e32 v2, v2, v3
	v_add_f32_e32 v6, v2, v6
	v_mov_b32_e32 v8, v30
	v_mov_b32_e32 v9, v31
	s_cbranch_scc0 .LBB0_548
	v_and_b32_e32 v1, 64, v204
	v_xor_b32_e32 v0, 1, v204
	v_add_u32_e32 v1, 64, v1
	v_cmp_lt_i32_e32 vcc, v0, v1
	s_nop 1
	v_cndmask_b32_e32 v0, v204, v0, vcc
	v_lshlrev_b32_e32 v0, 2, v0
	ds_bpermute_b32 v0, v0, v6
	v_cmp_eq_u32_e32 vcc, 0, v5
	s_and_saveexec_b64 s[0:1], vcc
	s_cbranch_execz .LBB0_551
	s_waitcnt lgkmcnt(0)
	v_add_f32_e32 v0, v6, v0
	v_fmamk_f32 v0, v0, 0x3b800000, v134
	v_mul_f32_e32 v1, 0x4b800000, v0
	v_cmp_gt_f32_e32 vcc, s33, v0
	s_nop 1
	v_cndmask_b32_e32 v0, v0, v1, vcc
	v_rsq_f32_e32 v0, v0
	s_nop 0
	v_mul_f32_e32 v1, 0x45800000, v0
	v_cndmask_b32_e32 v0, v0, v1, vcc
	v_lshl_add_u32 v1, v4, 2, v210
	ds_write_b32 v1, v0

; DI float bflo(unsigned v) { return __uint_as_float(v << 16); }
; DI float bfhi(unsigned v) { return __uint_as_float(v & 0xffff0000u); }
;     ...
;     {
;       const int tok = tid >> 2, qu = tid & 3;
;       const u16* p = projA + (size_t)(T0 + tok) * 1024 + 512 + qu * 128;
;       float s1 = 0.f, s2 = 0.f;
; #pragma unroll
;       for (int i = 0; i < 16; ++i) {
;         i32x4 v = *(const i32x4*)(p + i * 8);
; #pragma unroll
;         for (int e = 0; e < 4; ++e) {
;           float a = bflo((unsigned)v[e]), c = bfhi((unsigned)v[e]);
;           s1 += a + c;
;           s2 += a * a + c * c;
;         }
;       }
;       s1 += __shfl_xor(s1, 1); s2 += __shfl_xor(s2, 1);
;       s1 += __shfl_xor(s1, 2); s2 += __shfl_xor(s2, 2);
;       const float mean = s1 * (1.f / 512.f);
;       const float var = fmaxf(s2 * (1.f / 512.f) - mean * mean, 0.f);
;       if (qu == 0) { st[tok] = mean; st[128 + tok] = rsqrtf(var + EPS); }
;     }
.LBB0_778:
	v_lshl_add_u32 v0, s4, 7, v29
	v_ashrrev_i32_e32 v1, 31, v0
	v_lshlrev_b64 v[0:1], 11, v[0:1]
	v_lshl_add_u64 v[0:1], s[12:13], 0, v[0:1]
	v_lshl_add_u64 v[0:1], v[0:1], 0, v[132:133]
	global_load_dwordx4 v[136:139], v[0:1], off offset:1024
	global_load_dwordx4 v[140:143], v[0:1], off offset:1040
	global_load_dwordx4 v[144:147], v[0:1], off offset:1056
	global_load_dwordx4 v[148:151], v[0:1], off offset:1072
	global_load_dwordx4 v[152:155], v[0:1], off offset:1088
	global_load_dwordx4 v[156:159], v[0:1], off offset:1104
	global_load_dwordx4 v[160:163], v[0:1], off offset:1120
	global_load_dwordx4 v[164:167], v[0:1], off offset:1136
	global_load_dwordx4 v[168:171], v[0:1], off offset:1152
	global_load_dwordx4 v[172:175], v[0:1], off offset:1168
	global_load_dwordx4 v[176:179], v[0:1], off offset:1184
	global_load_dwordx4 v[180:183], v[0:1], off offset:1216
	global_load_dwordx4 v[184:187], v[0:1], off offset:1200
	global_load_dwordx4 v[188:191], v[0:1], off offset:1232
	global_load_dwordx4 v[192:195], v[0:1], off offset:1248
	global_load_dwordx4 v[196:199], v[0:1], off offset:1264
	s_waitcnt vmcnt(15) lgkmcnt(0)
	v_lshlrev_b32_e32 v11, 16, v137
	v_and_b32_e32 v7, 0xffff0000, v136
	v_lshlrev_b32_e32 v10, 16, v136
	v_mov_b32_e32 v2, v11
	v_and_b32_e32 v9, 0xffff0000, v137
	v_mov_b32_e32 v3, v137
	v_pk_mul_f32 v[36:37], v[10:11], v[2:3] op_sel:[1,0] op_sel_hi:[0,1]
	v_pk_add_f32 v[2:3], v[10:11], v[6:7] op_sel:[1,0] op_sel_hi:[0,1]
	v_mov_b32_e32 v37, v3
	v_lshlrev_b32_e32 v39, 16, v138
	v_and_b32_e32 v41, 0xffff0000, v138
	v_lshlrev_b32_e32 v43, 16, v139
	v_and_b32_e32 v45, 0xffff0000, v139
	v_mul_f32_e32 v34, v10, v10
	v_mul_f32_e32 v6, v9, v9
	v_mov_b32_e32 v35, v11
	v_mul_f32_e32 v8, v7, v7
	v_mov_b32_e32 v7, v133
	v_mul_f32_e32 v38, v39, v39
	v_mul_f32_e32 v40, v41, v41
	v_pk_add_f32 v[8:9], v[34:35], v[8:9]
	v_pk_add_f32 v[6:7], v[36:37], v[6:7]
	v_mul_f32_e32 v42, v43, v43
	v_mul_f32_e32 v44, v45, v45
	v_pk_add_f32 v[6:7], v[8:9], v[6:7]
	v_pk_add_f32 v[8:9], v[38:39], v[40:41]
	s_waitcnt vmcnt(14) lgkmcnt(0)
	v_lshlrev_b32_e32 v47, 16, v140
	v_and_b32_e32 v49, 0xffff0000, v140
	v_lshlrev_b32_e32 v51, 16, v141
	v_and_b32_e32 v53, 0xffff0000, v141
	v_lshlrev_b32_e32 v55, 16, v142
	v_and_b32_e32 v57, 0xffff0000, v142
	v_lshlrev_b32_e32 v59, 16, v143
	v_and_b32_e32 v61, 0xffff0000, v143
	v_mul_f32_e32 v46, v47, v47
	v_mul_f32_e32 v48, v49, v49
	v_pk_add_f32 v[6:7], v[8:9], v[6:7]
	v_pk_add_f32 v[8:9], v[42:43], v[44:45]
	v_mul_f32_e32 v50, v51, v51
	v_mul_f32_e32 v52, v53, v53
	v_pk_add_f32 v[6:7], v[8:9], v[6:7]
	v_pk_add_f32 v[8:9], v[46:47], v[48:49]
	v_mul_f32_e32 v54, v55, v55
	v_mul_f32_e32 v56, v57, v57
	v_pk_add_f32 v[6:7], v[8:9], v[6:7]
	v_pk_add_f32 v[8:9], v[50:51], v[52:53]
	v_mul_f32_e32 v58, v59, v59
	v_mul_f32_e32 v60, v61, v61
	v_pk_add_f32 v[6:7], v[8:9], v[6:7]
	v_pk_add_f32 v[8:9], v[54:55], v[56:57]
	s_waitcnt vmcnt(13) lgkmcnt(0)
	v_lshlrev_b32_e32 v63, 16, v144
	v_and_b32_e32 v105, 0xffff0000, v144
	v_mul_f32_e32 v62, v63, v63
	v_mul_f32_e32 v104, v105, v105
	v_lshlrev_b32_e32 v107, 16, v145
	v_and_b32_e32 v3, 0xffff0000, v145
	v_pk_add_f32 v[6:7], v[8:9], v[6:7]
	v_pk_add_f32 v[8:9], v[58:59], v[60:61]
	v_mul_f32_e32 v106, v107, v107
	v_mul_f32_e32 v2, v3, v3
	v_lshlrev_b32_e32 v109, 16, v146
	v_and_b32_e32 v111, 0xffff0000, v146
	v_pk_add_f32 v[6:7], v[8:9], v[6:7]
	v_pk_add_f32 v[8:9], v[62:63], v[104:105]
	v_mul_f32_e32 v108, v109, v109
	v_mul_f32_e32 v110, v111, v111
	v_pk_add_f32 v[6:7], v[8:9], v[6:7]
	v_pk_add_f32 v[2:3], v[106:107], v[2:3]
	s_nop 0
	v_pk_add_f32 v[2:3], v[2:3], v[6:7]
	v_pk_add_f32 v[6:7], v[108:109], v[110:111]
	s_nop 0
	v_pk_add_f32 v[2:3], v[6:7], v[2:3]
	v_lshlrev_b32_e32 v7, 16, v147
	v_and_b32_e32 v5, 0xffff0000, v147
	v_mul_f32_e32 v6, v7, v7
	v_mul_f32_e32 v4, v5, v5
	v_pk_add_f32 v[4:5], v[6:7], v[4:5]
	v_pk_add_f32 v[2:3], v[4:5], v[2:3]
	s_waitcnt vmcnt(12) lgkmcnt(0)
	v_lshlrev_b32_e32 v11, 16, v148
	v_and_b32_e32 v35, 0xffff0000, v148
	v_lshlrev_b32_e32 v37, 16, v149
	v_and_b32_e32 v39, 0xffff0000, v149
	v_lshlrev_b32_e32 v41, 16, v150
	v_and_b32_e32 v43, 0xffff0000, v150
	v_lshlrev_b32_e32 v45, 16, v151
	v_and_b32_e32 v47, 0xffff0000, v151
	v_mul_f32_e32 v10, v11, v11
	v_mul_f32_e32 v34, v35, v35
	v_mul_f32_e32 v36, v37, v37
	v_mul_f32_e32 v38, v39, v39
	v_pk_add_f32 v[4:5], v[10:11], v[34:35]
	v_mul_f32_e32 v40, v41, v41
	v_mul_f32_e32 v42, v43, v43
	v_pk_add_f32 v[2:3], v[4:5], v[2:3]
	v_pk_add_f32 v[4:5], v[36:37], v[38:39]
	v_mul_f32_e32 v44, v45, v45
	v_mul_f32_e32 v46, v47, v47
	v_pk_add_f32 v[2:3], v[4:5], v[2:3]
	v_pk_add_f32 v[4:5], v[40:41], v[42:43]
	s_waitcnt vmcnt(11) lgkmcnt(0)
	v_lshlrev_b32_e32 v49, 16, v152
	v_and_b32_e32 v51, 0xffff0000, v152
	v_lshlrev_b32_e32 v53, 16, v153
	v_and_b32_e32 v55, 0xffff0000, v153
	v_lshlrev_b32_e32 v57, 16, v154
	v_and_b32_e32 v59, 0xffff0000, v154
	v_lshlrev_b32_e32 v61, 16, v155
	v_and_b32_e32 v63, 0xffff0000, v155
	v_pk_add_f32 v[2:3], v[4:5], v[2:3]
	v_pk_add_f32 v[4:5], v[44:45], v[46:47]
	v_mul_f32_e32 v48, v49, v49
	v_mul_f32_e32 v50, v51, v51
	v_mul_f32_e32 v52, v53, v53
	v_mul_f32_e32 v54, v55, v55
	v_pk_add_f32 v[2:3], v[4:5], v[2:3]
	v_pk_add_f32 v[4:5], v[48:49], v[50:51]
	v_mul_f32_e32 v56, v57, v57
	v_mul_f32_e32 v58, v59, v59
	v_pk_add_f32 v[2:3], v[4:5], v[2:3]
	v_pk_add_f32 v[4:5], v[52:53], v[54:55]
	v_mul_f32_e32 v60, v61, v61
	v_mul_f32_e32 v62, v63, v63
	v_pk_add_f32 v[2:3], v[4:5], v[2:3]
	v_pk_add_f32 v[4:5], v[56:57], v[58:59]
	s_waitcnt vmcnt(9) lgkmcnt(0)
; DI float bflo(unsigned v) { return __uint_as_float(v << 16); }
; DI float bfhi(unsigned v) { return __uint_as_float(v & 0xffff0000u); }
;     ...
;     {
;       const int tok = tid >> 2, qu = tid & 3;
;       const u16* p = projA + (size_t)(T0 + tok) * 1024 + 512 + qu * 128;
;       float s1 = 0.f, s2 = 0.f;
; #pragma unroll
;       for (int i = 0; i < 16; ++i) {
;         i32x4 v = *(const i32x4*)(p + i * 8);
; #pragma unroll
;         for (int e = 0; e < 4; ++e) {
;           float a = bflo((unsigned)v[e]), c = bfhi((unsigned)v[e]);
;           s1 += a + c;
;           s2 += a * a + c * c;
;         }
;       }
;       s1 += __shfl_xor(s1, 1); s2 += __shfl_xor(s2, 1);
;       s1 += __shfl_xor(s1, 2); s2 += __shfl_xor(s2, 2);
;       const float mean = s1 * (1.f / 512.f);
;       const float var = fmaxf(s2 * (1.f / 512.f) - mean * mean, 0.f);
;       if (qu == 0) { st[tok] = mean; st[128 + tok] = rsqrtf(var + EPS); }
;     }
	v_lshlrev_b32_e32 v105, 16, v156
	v_and_b32_e32 v107, 0xffff0000, v156
	v_mul_f32_e32 v104, v105, v105
	v_mul_f32_e32 v106, v107, v107
	v_lshlrev_b32_e32 v109, 16, v157
	v_and_b32_e32 v7, 0xffff0000, v157
	v_pk_add_f32 v[2:3], v[4:5], v[2:3]
	v_pk_add_f32 v[4:5], v[60:61], v[62:63]
	v_mul_f32_e32 v108, v109, v109
	v_mul_f32_e32 v6, v7, v7
	v_pk_add_f32 v[2:3], v[4:5], v[2:3]
	v_pk_add_f32 v[4:5], v[104:105], v[106:107]
	v_lshlrev_b32_e32 v11, 16, v160
	v_pk_add_f32 v[2:3], v[4:5], v[2:3]
	v_pk_add_f32 v[4:5], v[108:109], v[6:7]
	v_and_b32_e32 v7, 0xffff0000, v158
	v_pk_add_f32 v[2:3], v[4:5], v[2:3]
	v_lshlrev_b32_e32 v5, 16, v158
	v_mul_f32_e32 v4, v5, v5
	v_mul_f32_e32 v6, v7, v7
	v_pk_add_f32 v[4:5], v[4:5], v[6:7]
	v_lshlrev_b32_e32 v7, 16, v159
	v_and_b32_e32 v9, 0xffff0000, v159
	v_mul_f32_e32 v6, v7, v7
	v_mul_f32_e32 v8, v9, v9
	v_and_b32_e32 v35, 0xffff0000, v160
	v_mul_f32_e32 v10, v11, v11
	v_mul_f32_e32 v34, v35, v35
	v_lshlrev_b32_e32 v37, 16, v161
	v_and_b32_e32 v39, 0xffff0000, v161
	v_pk_add_f32 v[2:3], v[4:5], v[2:3]
	v_pk_add_f32 v[4:5], v[6:7], v[8:9]
	v_mul_f32_e32 v36, v37, v37
	v_mul_f32_e32 v38, v39, v39
	v_pk_add_f32 v[2:3], v[4:5], v[2:3]
	v_pk_add_f32 v[4:5], v[10:11], v[34:35]
	v_pk_add_f32 v[2:3], v[4:5], v[2:3]
	v_pk_add_f32 v[4:5], v[36:37], v[38:39]
	v_lshlrev_b32_e32 v41, 16, v162
	v_and_b32_e32 v43, 0xffff0000, v162
	v_mul_f32_e32 v40, v41, v41
	v_mul_f32_e32 v42, v43, v43
	v_lshlrev_b32_e32 v45, 16, v163
	v_and_b32_e32 v47, 0xffff0000, v163
	v_mul_f32_e32 v44, v45, v45
	v_mul_f32_e32 v46, v47, v47
	v_pk_add_f32 v[2:3], v[4:5], v[2:3]
	v_pk_add_f32 v[4:5], v[40:41], v[42:43]
	s_waitcnt vmcnt(6) lgkmcnt(0)
	v_lshlrev_b32_e32 v49, 16, v164
	v_and_b32_e32 v51, 0xffff0000, v164
	v_mul_f32_e32 v48, v49, v49
	v_mul_f32_e32 v50, v51, v51
	v_lshlrev_b32_e32 v53, 16, v165
	v_and_b32_e32 v55, 0xffff0000, v165
	v_pk_add_f32 v[2:3], v[4:5], v[2:3]
	v_pk_add_f32 v[4:5], v[44:45], v[46:47]
	v_mul_f32_e32 v52, v53, v53
	v_mul_f32_e32 v54, v55, v55
	v_pk_add_f32 v[2:3], v[4:5], v[2:3]
	v_pk_add_f32 v[4:5], v[48:49], v[50:51]
	v_lshlrev_b32_e32 v57, 16, v166
	v_pk_add_f32 v[2:3], v[4:5], v[2:3]
	v_pk_add_f32 v[4:5], v[52:53], v[54:55]
	v_lshlrev_b32_e32 v41, 16, v172
	v_and_b32_e32 v43, 0xffff0000, v172
	v_lshlrev_b32_e32 v45, 16, v173
	v_and_b32_e32 v47, 0xffff0000, v173
	v_lshlrev_b32_e32 v49, 16, v174
	v_and_b32_e32 v51, 0xffff0000, v174
	v_lshlrev_b32_e32 v53, 16, v175
	v_and_b32_e32 v55, 0xffff0000, v175
	v_and_b32_e32 v59, 0xffff0000, v166
	v_mul_f32_e32 v56, v57, v57
	v_mul_f32_e32 v58, v59, v59
	v_lshlrev_b32_e32 v61, 16, v167
	v_and_b32_e32 v63, 0xffff0000, v167
	v_mul_f32_e32 v60, v61, v61
	v_mul_f32_e32 v62, v63, v63
	v_lshlrev_b32_e32 v109, 16, v168
	v_and_b32_e32 v111, 0xffff0000, v168
	v_pk_add_f32 v[2:3], v[4:5], v[2:3]
	v_pk_add_f32 v[4:5], v[56:57], v[58:59]
	v_mul_f32_e32 v108, v109, v109
	v_mul_f32_e32 v110, v111, v111
	v_pk_add_f32 v[2:3], v[4:5], v[2:3]
	v_pk_add_f32 v[4:5], v[60:61], v[62:63]
	v_and_b32_e32 v7, 0xffff0000, v169
	v_pk_add_f32 v[2:3], v[4:5], v[2:3]
	v_pk_add_f32 v[4:5], v[108:109], v[110:111]
	v_mul_f32_e32 v6, v7, v7
	v_pk_add_f32 v[2:3], v[4:5], v[2:3]
	v_lshlrev_b32_e32 v5, 16, v169
	v_mul_f32_e32 v4, v5, v5
	v_pk_add_f32 v[4:5], v[4:5], v[6:7]
	v_lshlrev_b32_e32 v7, 16, v170
	v_and_b32_e32 v9, 0xffff0000, v170
	v_mul_f32_e32 v6, v7, v7
	v_mul_f32_e32 v8, v9, v9
	v_lshlrev_b32_e32 v11, 16, v171
	v_and_b32_e32 v35, 0xffff0000, v171
	v_mul_f32_e32 v10, v11, v11
	v_mul_f32_e32 v34, v35, v35
	v_pk_add_f32 v[2:3], v[4:5], v[2:3]
	v_pk_add_f32 v[4:5], v[6:7], v[8:9]
	v_mul_f32_e32 v40, v41, v41
	v_mul_f32_e32 v42, v43, v43
	v_pk_add_f32 v[2:3], v[4:5], v[2:3]
	v_pk_add_f32 v[4:5], v[10:11], v[34:35]
	v_mul_f32_e32 v44, v45, v45
	v_pk_add_f32 v[2:3], v[4:5], v[2:3]
	v_pk_add_f32 v[4:5], v[40:41], v[42:43]
	v_mul_f32_e32 v46, v47, v47
	v_mul_f32_e32 v48, v49, v49
	v_mul_f32_e32 v50, v51, v51
	v_pk_add_f32 v[2:3], v[4:5], v[2:3]
	v_pk_add_f32 v[4:5], v[44:45], v[46:47]
	v_mul_f32_e32 v52, v53, v53
	v_mul_f32_e32 v54, v55, v55
	v_pk_add_f32 v[2:3], v[4:5], v[2:3]
	v_pk_add_f32 v[4:5], v[48:49], v[50:51]
	s_waitcnt vmcnt(4) lgkmcnt(0)
	v_lshlrev_b32_e32 v57, 16, v176
	v_and_b32_e32 v59, 0xffff0000, v176
	v_mul_f32_e32 v56, v57, v57
	v_mul_f32_e32 v58, v59, v59
	v_lshlrev_b32_e32 v61, 16, v177
	v_and_b32_e32 v37, 0xffff0000, v177
	v_pk_add_f32 v[2:3], v[4:5], v[2:3]
	v_pk_add_f32 v[4:5], v[52:53], v[54:55]
	v_mul_f32_e32 v60, v61, v61
	v_mul_f32_e32 v36, v37, v37
	v_lshlrev_b32_e32 v63, 16, v178
	v_and_b32_e32 v105, 0xffff0000, v178
	v_pk_add_f32 v[2:3], v[4:5], v[2:3]
	v_pk_add_f32 v[4:5], v[56:57], v[58:59]
	v_mul_f32_e32 v62, v63, v63
	v_mul_f32_e32 v104, v105, v105
	v_lshlrev_b32_e32 v107, 16, v179
	v_and_b32_e32 v39, 0xffff0000, v179
	v_pk_add_f32 v[2:3], v[4:5], v[2:3]
	v_pk_add_f32 v[4:5], v[60:61], v[36:37]
	v_mul_f32_e32 v106, v107, v107
	v_mul_f32_e32 v38, v39, v39
	v_pk_add_f32 v[2:3], v[4:5], v[2:3]
	v_pk_add_f32 v[4:5], v[62:63], v[104:105]
	v_lshlrev_b32_e32 v45, 16, v180
	v_pk_add_f32 v[2:3], v[4:5], v[2:3]
	v_pk_add_f32 v[4:5], v[106:107], v[38:39]
	v_and_b32_e32 v47, 0xffff0000, v180
	v_lshlrev_b32_e32 v49, 16, v181
	v_and_b32_e32 v51, 0xffff0000, v181
	v_lshlrev_b32_e32 v53, 16, v182
	v_and_b32_e32 v55, 0xffff0000, v182
	v_lshlrev_b32_e32 v57, 16, v183
	v_and_b32_e32 v59, 0xffff0000, v183
	v_pk_add_f32 v[2:3], v[4:5], v[2:3]
	v_mul_f32_e32 v44, v45, v45
	v_mul_f32_e32 v46, v47, v47
	v_mul_f32_e32 v48, v49, v49
	v_mul_f32_e32 v50, v51, v51
	v_mul_f32_e32 v52, v53, v53
	v_mul_f32_e32 v54, v55, v55
	v_mul_f32_e32 v56, v57, v57
	v_mul_f32_e32 v58, v59, v59
	s_waitcnt vmcnt(2) lgkmcnt(0)
; DI float bflo(unsigned v) { return __uint_as_float(v << 16); }
; DI float bfhi(unsigned v) { return __uint_as_float(v & 0xffff0000u); }
;     ...
;     {
;       const int tok = tid >> 2, qu = tid & 3;
;       const u16* p = projA + (size_t)(T0 + tok) * 1024 + 512 + qu * 128;
;       float s1 = 0.f, s2 = 0.f;
; #pragma unroll
;       for (int i = 0; i < 16; ++i) {
;         i32x4 v = *(const i32x4*)(p + i * 8);
; #pragma unroll
;         for (int e = 0; e < 4; ++e) {
;           float a = bflo((unsigned)v[e]), c = bfhi((unsigned)v[e]);
;           s1 += a + c;
;           s2 += a * a + c * c;
;         }
;       }
;       s1 += __shfl_xor(s1, 1); s2 += __shfl_xor(s2, 1);
;       s1 += __shfl_xor(s1, 2); s2 += __shfl_xor(s2, 2);
;       const float mean = s1 * (1.f / 512.f);
;       const float var = fmaxf(s2 * (1.f / 512.f) - mean * mean, 0.f);
;       if (qu == 0) { st[tok] = mean; st[128 + tok] = rsqrtf(var + EPS); }
;     }
	v_lshlrev_b32_e32 v5, 16, v184
	v_and_b32_e32 v7, 0xffff0000, v184
	v_mul_f32_e32 v4, v5, v5
	v_mul_f32_e32 v6, v7, v7
	v_pk_add_f32 v[4:5], v[4:5], v[6:7]
	v_lshlrev_b32_e32 v7, 16, v185
	v_and_b32_e32 v9, 0xffff0000, v185
	v_mul_f32_e32 v6, v7, v7
	v_mul_f32_e32 v8, v9, v9
	v_lshlrev_b32_e32 v11, 16, v186
	v_and_b32_e32 v35, 0xffff0000, v186
	v_mul_f32_e32 v10, v11, v11
	v_mul_f32_e32 v34, v35, v35
	v_lshlrev_b32_e32 v37, 16, v187
	v_and_b32_e32 v39, 0xffff0000, v187
	v_pk_add_f32 v[2:3], v[4:5], v[2:3]
	v_pk_add_f32 v[4:5], v[6:7], v[8:9]
	v_mul_f32_e32 v36, v37, v37
	v_mul_f32_e32 v38, v39, v39
	v_pk_add_f32 v[2:3], v[4:5], v[2:3]
	v_pk_add_f32 v[4:5], v[10:11], v[34:35]
	v_lshlrev_b32_e32 v61, 16, v188
	v_pk_add_f32 v[2:3], v[4:5], v[2:3]
	v_pk_add_f32 v[4:5], v[36:37], v[38:39]
	v_and_b32_e32 v63, 0xffff0000, v188
	v_pk_add_f32 v[2:3], v[4:5], v[2:3]
	v_pk_add_f32 v[4:5], v[44:45], v[46:47]
	v_mul_f32_e32 v60, v61, v61
	v_pk_add_f32 v[2:3], v[4:5], v[2:3]
	v_pk_add_f32 v[4:5], v[48:49], v[50:51]
	v_mul_f32_e32 v62, v63, v63
	v_pk_add_f32 v[2:3], v[4:5], v[2:3]
	v_pk_add_f32 v[4:5], v[52:53], v[54:55]
	v_lshlrev_b32_e32 v105, 16, v189
	v_and_b32_e32 v41, 0xffff0000, v189
	v_pk_add_f32 v[2:3], v[4:5], v[2:3]
	v_pk_add_f32 v[4:5], v[56:57], v[58:59]
	v_mul_f32_e32 v104, v105, v105
	v_mul_f32_e32 v40, v41, v41
	v_lshlrev_b32_e32 v107, 16, v190
	v_and_b32_e32 v109, 0xffff0000, v190
	v_pk_add_f32 v[2:3], v[4:5], v[2:3]
	v_pk_add_f32 v[4:5], v[60:61], v[62:63]
	v_mul_f32_e32 v106, v107, v107
	v_mul_f32_e32 v108, v109, v109
	v_pk_add_f32 v[2:3], v[4:5], v[2:3]
	v_pk_add_f32 v[4:5], v[104:105], v[40:41]
	v_pk_add_f32 v[2:3], v[4:5], v[2:3]
	v_pk_add_f32 v[4:5], v[106:107], v[108:109]
	v_and_b32_e32 v7, 0xffff0000, v191
	v_pk_add_f32 v[4:5], v[4:5], v[2:3]
	v_lshlrev_b32_e32 v3, 16, v191
	v_mul_f32_e32 v2, v3, v3
	v_mul_f32_e32 v6, v7, v7
	v_pk_add_f32 v[6:7], v[2:3], v[6:7]
	v_pk_add_f32 v[4:5], v[6:7], v[4:5]
	s_waitcnt vmcnt(0) lgkmcnt(0)
	v_lshlrev_b32_e32 v43, 16, v192
	v_and_b32_e32 v45, 0xffff0000, v192
	v_mul_f32_e32 v42, v43, v43
	v_mul_f32_e32 v44, v45, v45
	v_lshlrev_b32_e32 v39, 16, v193
	v_and_b32_e32 v41, 0xffff0000, v193
	v_mul_f32_e32 v38, v39, v39
	v_mul_f32_e32 v40, v41, v41
	v_lshlrev_b32_e32 v35, 16, v194
	v_and_b32_e32 v37, 0xffff0000, v194
	v_pk_add_f32 v[6:7], v[42:43], v[44:45]
	v_mul_f32_e32 v34, v35, v35
	v_mul_f32_e32 v36, v37, v37
	v_lshlrev_b32_e32 v9, 16, v195
	v_and_b32_e32 v11, 0xffff0000, v195
	v_pk_add_f32 v[4:5], v[6:7], v[4:5]
	v_pk_add_f32 v[6:7], v[38:39], v[40:41]
	v_mul_f32_e32 v8, v9, v9
	v_mul_f32_e32 v10, v11, v11
	v_lshlrev_b32_e32 v47, 16, v196
	v_and_b32_e32 v49, 0xffff0000, v196
	v_pk_add_f32 v[4:5], v[6:7], v[4:5]
	v_pk_add_f32 v[6:7], v[34:35], v[36:37]
	v_mul_f32_e32 v46, v47, v47
	v_mul_f32_e32 v48, v49, v49
	v_lshlrev_b32_e32 v51, 16, v197
	v_and_b32_e32 v1, 0xffff0000, v197
	v_pk_add_f32 v[4:5], v[6:7], v[4:5]
	v_pk_add_f32 v[6:7], v[8:9], v[10:11]
	v_mul_f32_e32 v50, v51, v51
	v_mul_f32_e32 v0, v1, v1
	v_lshlrev_b32_e32 v53, 16, v198
	v_and_b32_e32 v55, 0xffff0000, v198
	v_pk_add_f32 v[4:5], v[6:7], v[4:5]
	v_pk_add_f32 v[6:7], v[46:47], v[48:49]
	v_mul_f32_e32 v52, v53, v53
	v_mul_f32_e32 v54, v55, v55
	v_lshlrev_b32_e32 v57, 16, v199
	v_and_b32_e32 v3, 0xffff0000, v199
	v_pk_add_f32 v[4:5], v[6:7], v[4:5]
	v_pk_add_f32 v[0:1], v[50:51], v[0:1]
	v_mul_f32_e32 v56, v57, v57
	v_mul_f32_e32 v2, v3, v3
	v_pk_add_f32 v[0:1], v[0:1], v[4:5]
	v_pk_add_f32 v[4:5], v[52:53], v[54:55]
	v_pk_add_f32 v[2:3], v[56:57], v[2:3]
	v_pk_add_f32 v[0:1], v[4:5], v[0:1]
	s_nop 0
	v_pk_add_f32 v[0:1], v[2:3], v[0:1]
	ds_bpermute_b32 v3, v216, v1
	ds_bpermute_b32 v2, v216, v0
	s_waitcnt lgkmcnt(0)
	v_pk_add_f32 v[0:1], v[0:1], v[2:3]
	ds_bpermute_b32 v3, v215, v1
	ds_bpermute_b32 v2, v215, v0
	s_and_saveexec_b64 s[0:1], s[8:9]
	s_cbranch_execz .LBB0_780
	s_waitcnt lgkmcnt(0)
	v_pk_add_f32 v[0:1], v[0:1], v[2:3]
	s_mov_b32 s16, 0x3b000000
	v_pk_mul_f32 v[0:1], v[0:1], s[16:17] op_sel_hi:[1,0]
	s_nop 0
	v_fma_f32 v0, -v1, v1, v0
	v_max_f32_e32 v0, 0, v0
	v_add_f32_e32 v0, 0x358637bd, v0
	v_mul_f32_e32 v2, 0x4b800000, v0
	v_cmp_gt_f32_e32 vcc, s33, v0
	s_nop 1
	v_cndmask_b32_e32 v0, v0, v2, vcc
	v_rsq_f32_e32 v0, v0
	s_nop 0
	v_mul_f32_e32 v2, 0x45800000, v0
	v_cndmask_b32_e32 v0, v0, v2, vcc
	ds_write2st64_b32 v64, v1, v0 offset0:136 offset1:138

; DI u16 f2bf(float a) { return (u16)(pack2(a, 0.f) & 0xffffu); }
; DI float bflo(unsigned v) { return __uint_as_float(v << 16); }
; DI float bfhi(unsigned v) { return __uint_as_float(v & 0xffff0000u); }
;     ...
;       {
;         const int s = tid >> 2, cq = tid & 3;
;         const float mean = st[s], rstd = st[128 + s];
;         const u16* p = projA + (size_t)(T0 + s) * 1024 + 512 + g * 128 + cq * 32;
; #pragma unroll
;         for (int i = 0; i < 4; ++i) {
;           i32x4 v = *(const i32x4*)(p + i * 8);
; #pragma unroll
;           for (int e = 0; e < 4; ++e) {
;             const int c = cq * 32 + i * 8 + 2 * e;
;             float a = (bflo((unsigned)v[e]) - mean) * rstd * lng[g * 128 + c] + lnb[g * 128 + c];
;             float d = (bfhi((unsigned)v[e]) - mean) * rstd * lng[g * 128 + c + 1] + lnb[g * 128 + c + 1];
;             vT[c * 136 + s] = f2bf(a);
;             vT[(c + 1) * 136 + s] = f2bf(d);
;           }
;         }
;       }
.LBB0_781:
	v_lshl_add_u64 v[2:3], s[18:19], 0, v[42:43]
	v_add_co_u32_e32 v10, vcc, 0x19000000, v2
	ds_read2st64_b32 v[0:1], v64 offset0:136 offset1:138
	s_nop 0
	v_addc_co_u32_e32 v11, vcc, 0, v3, vcc
	global_load_dwordx4 v[136:139], v[10:11], off offset:1024
	global_load_dwordx4 v[140:143], v[10:11], off offset:1040
	global_load_dwordx4 v[144:147], v[10:11], off offset:1056
	global_load_dwordx4 v[148:151], v[10:11], off offset:1072
	v_lshl_add_u64 v[62:63], v[24:25], 0, s[16:17]
	v_lshl_add_u64 v[124:125], v[26:27], 0, s[16:17]
	v_ashrrev_i32_e32 v53, 31, v52
	s_add_u32 s16, s16, 0x200
	s_addc_u32 s17, s17, 0
	s_waitcnt vmcnt(3) lgkmcnt(0)
	v_lshlrev_b32_e32 v6, 16, v136
	v_sub_f32_e32 v6, v6, v0
	v_mul_f32_e32 v17, v1, v6
	global_load_dwordx4 v[6:9], v[62:63], off offset:48
	global_load_dwordx4 v[54:57], v[62:63], off offset:32
	global_load_dwordx4 v[58:61], v[62:63], off offset:16
	global_load_dwordx4 v[104:107], v[62:63], off
	global_load_dwordx4 v[108:111], v[124:125], off offset:48
	global_load_dwordx4 v[112:115], v[124:125], off offset:32
	global_load_dwordx4 v[116:119], v[124:125], off offset:16
	global_load_dwordx4 v[120:123], v[124:125], off
	v_and_b32_e32 v2, 0xffff0000, v136
	v_sub_f32_e32 v2, v2, v0
	v_mul_f32_e32 v2, v1, v2
	s_waitcnt vmcnt(0)
	v_fma_f32 v17, v104, v17, v120
	v_fma_f32 v2, v105, v2, v121
	v_cvt_pk_bf16_f32 v17, v17, s0
	v_cvt_pk_bf16_f32 v2, v2, s0
	ds_write_b16 v66, v17
	ds_write_b16 v67, v2 offset:272
	v_lshlrev_b32_e32 v2, 16, v137
	v_sub_f32_e32 v2, v2, v0
	v_and_b32_e32 v3, 0xffff0000, v137
	v_mul_f32_e32 v2, v1, v2
	v_sub_f32_e32 v3, v3, v0
	v_fma_f32 v2, v2, v106, v122
	v_mul_f32_e32 v3, v1, v3
	v_fmac_f32_e32 v123, v3, v107
	v_cvt_pk_bf16_f32 v2, v2, s0
	ds_write_b16 v68, v2
	v_cvt_pk_bf16_f32 v2, v123, s0
	ds_write_b16 v69, v2 offset:272
	v_lshlrev_b32_e32 v2, 16, v138
	v_sub_f32_e32 v2, v2, v0
	v_and_b32_e32 v3, 0xffff0000, v138
	v_mul_f32_e32 v2, v1, v2
	v_sub_f32_e32 v3, v3, v0
	v_fma_f32 v2, v2, v58, v116
	v_mul_f32_e32 v3, v1, v3
	v_fma_f32 v3, v3, v59, v117
	v_cvt_pk_bf16_f32 v2, v2, s0
	ds_write_b16 v70, v2
	v_cvt_pk_bf16_f32 v2, v3, s0
	ds_write_b16 v71, v2 offset:272
	v_lshlrev_b32_e32 v2, 16, v139
	v_sub_f32_e32 v2, v2, v0
	v_and_b32_e32 v3, 0xffff0000, v139
	v_mul_f32_e32 v2, v1, v2
	v_sub_f32_e32 v3, v3, v0
	v_fma_f32 v2, v2, v60, v118
	v_mul_f32_e32 v3, v1, v3
	v_fmac_f32_e32 v119, v3, v61
	v_cvt_pk_bf16_f32 v2, v2, s0
	ds_write_b16 v72, v2
	v_cvt_pk_bf16_f32 v2, v119, s0
	ds_write_b16 v73, v2 offset:272
	s_waitcnt vmcnt(2) lgkmcnt(0)
	v_lshlrev_b32_e32 v17, 16, v140
	v_and_b32_e32 v2, 0xffff0000, v140
	v_sub_f32_e32 v17, v17, v0
	v_sub_f32_e32 v2, v2, v0
	v_mul_f32_e32 v17, v1, v17
	v_mul_f32_e32 v2, v1, v2
	v_fma_f32 v17, v54, v17, v112
	v_fma_f32 v2, v55, v2, v113
	v_cvt_pk_bf16_f32 v17, v17, s0
	v_cvt_pk_bf16_f32 v2, v2, s0
	ds_write_b16 v74, v17
	ds_write_b16 v75, v2 offset:272
	v_lshlrev_b32_e32 v2, 16, v141
	v_sub_f32_e32 v2, v2, v0
	v_and_b32_e32 v3, 0xffff0000, v141
	v_mul_f32_e32 v2, v1, v2
	v_sub_f32_e32 v3, v3, v0
	v_fma_f32 v2, v2, v56, v114
	v_mul_f32_e32 v3, v1, v3
	v_fmac_f32_e32 v115, v3, v57
	v_cvt_pk_bf16_f32 v2, v2, s0
	ds_write_b16 v76, v2
	v_cvt_pk_bf16_f32 v2, v115, s0
	ds_write_b16 v77, v2 offset:272
	v_lshlrev_b32_e32 v2, 16, v142
	v_sub_f32_e32 v2, v2, v0
	v_and_b32_e32 v3, 0xffff0000, v142
	v_mul_f32_e32 v2, v1, v2
	v_sub_f32_e32 v3, v3, v0
	v_fma_f32 v2, v2, v6, v108
	v_mul_f32_e32 v3, v1, v3
	v_fma_f32 v3, v3, v7, v109
	v_cvt_pk_bf16_f32 v2, v2, s0
	ds_write_b16 v78, v2
	v_cvt_pk_bf16_f32 v2, v3, s0
	ds_write_b16 v79, v2 offset:272
	v_lshlrev_b32_e32 v2, 16, v143
	v_sub_f32_e32 v2, v2, v0
	v_and_b32_e32 v3, 0xffff0000, v143
	v_mul_f32_e32 v2, v1, v2
	v_sub_f32_e32 v3, v3, v0
	v_fma_f32 v2, v2, v8, v110
	v_mul_f32_e32 v3, v1, v3
	v_fmac_f32_e32 v111, v3, v9
	v_cvt_pk_bf16_f32 v2, v2, s0
	ds_write_b16 v80, v2
	v_cvt_pk_bf16_f32 v2, v111, s0
	ds_write_b16 v81, v2 offset:272
	s_waitcnt vmcnt(1) lgkmcnt(0)
	v_lshlrev_b32_e32 v6, 16, v144
	v_sub_f32_e32 v6, v6, v0
	v_mul_f32_e32 v17, v1, v6
	global_load_dwordx4 v[6:9], v[62:63], off offset:112
	global_load_dwordx4 v[54:57], v[62:63], off offset:96
	global_load_dwordx4 v[58:61], v[62:63], off offset:80
	global_load_dwordx4 v[104:107], v[62:63], off offset:64
	global_load_dwordx4 v[108:111], v[124:125], off offset:112
	global_load_dwordx4 v[112:115], v[124:125], off offset:96
	global_load_dwordx4 v[116:119], v[124:125], off offset:80
	global_load_dwordx4 v[120:123], v[124:125], off offset:64
	v_and_b32_e32 v2, 0xffff0000, v144
	v_sub_f32_e32 v2, v2, v0
	v_mul_f32_e32 v2, v1, v2
	s_waitcnt vmcnt(0)
	v_fma_f32 v17, v104, v17, v120
	v_fma_f32 v2, v105, v2, v121
	v_cvt_pk_bf16_f32 v17, v17, s0
	v_cvt_pk_bf16_f32 v2, v2, s0
	ds_write_b16 v82, v17
	ds_write_b16 v83, v2 offset:272
	v_lshlrev_b32_e32 v2, 16, v145
	v_sub_f32_e32 v2, v2, v0
	v_and_b32_e32 v3, 0xffff0000, v145
	v_mul_f32_e32 v2, v1, v2
	v_sub_f32_e32 v3, v3, v0
	v_fma_f32 v2, v2, v106, v122
	v_mul_f32_e32 v3, v1, v3
	v_fmac_f32_e32 v123, v3, v107
	v_cvt_pk_bf16_f32 v2, v2, s0
	ds_write_b16 v84, v2
	v_cvt_pk_bf16_f32 v2, v123, s0
	ds_write_b16 v85, v2 offset:272
	v_lshlrev_b32_e32 v2, 16, v146
	v_sub_f32_e32 v2, v2, v0
	v_and_b32_e32 v3, 0xffff0000, v146
	v_mul_f32_e32 v2, v1, v2
	v_sub_f32_e32 v3, v3, v0
	v_fma_f32 v2, v2, v58, v116
	v_mul_f32_e32 v3, v1, v3
	v_fma_f32 v3, v3, v59, v117
	v_cvt_pk_bf16_f32 v2, v2, s0
	ds_write_b16 v86, v2
	v_cvt_pk_bf16_f32 v2, v3, s0
	ds_write_b16 v87, v2 offset:272
	v_lshlrev_b32_e32 v2, 16, v147
	v_sub_f32_e32 v2, v2, v0
	v_and_b32_e32 v3, 0xffff0000, v147
	v_mul_f32_e32 v2, v1, v2
	v_sub_f32_e32 v3, v3, v0
	v_fma_f32 v2, v2, v60, v118
	v_mul_f32_e32 v3, v1, v3
	v_fmac_f32_e32 v119, v3, v61
	v_cvt_pk_bf16_f32 v2, v2, s0
	ds_write_b16 v88, v2
	v_cvt_pk_bf16_f32 v2, v119, s0
	ds_write_b16 v89, v2 offset:272
	s_waitcnt vmcnt(0) lgkmcnt(0)
; #define MFMA16(a, b, c) __builtin_amdgcn_mfma_f32_16x16x32_bf16((a), (b), (c), 0, 0, 0)
; DI u16 f2bf(float a) { return (u16)(pack2(a, 0.f) & 0xffffu); }
; DI float bflo(unsigned v) { return __uint_as_float(v << 16); }
; DI float bfhi(unsigned v) { return __uint_as_float(v & 0xffff0000u); }
;     ...
;         for (int i = 0; i < 4; ++i) {
;           i32x4 v = *(const i32x4*)(p + i * 8);
; #pragma unroll
;           for (int e = 0; e < 4; ++e) {
;             const int c = cq * 32 + i * 8 + 2 * e;
;             float a = (bflo((unsigned)v[e]) - mean) * rstd * lng[g * 128 + c] + lnb[g * 128 + c];
;             float d = (bfhi((unsigned)v[e]) - mean) * rstd * lng[g * 128 + c + 1] + lnb[g * 128 + c + 1];
;             vT[c * 136 + s] = f2bf(a);
;             vT[(c + 1) * 136 + s] = f2bf(d);
;           }
;         }
;       }
;       __syncthreads();
;       f32x4 acc[8];
; #pragma unroll
;       for (int i = 0; i < 8; ++i) acc[i] = f32x4{0.f, 0.f, 0.f, 0.f};
;       const u16* wp = Wsgu + (size_t)(g * 128 + wid * 16 + fr) * 128 + fq * 8;
; #pragma unroll
;       for (int ks = 0; ks < 4; ++ks) {
;         bf16x8 af = *(const bf16x8*)(wp + ks * 32);
; #pragma unroll
;         for (int ns = 0; ns < 8; ++ns) {
;           bf16x8 bfr = *(const bf16x8*)(vT + (ns * 16 + fr) * 136 + ks * 32 + fq * 8);
;           acc[ns] = MFMA16(bfr, af, acc[ns]);
;         }
;       }
	v_lshlrev_b32_e32 v10, 16, v148
	v_and_b32_e32 v2, 0xffff0000, v148
	v_sub_f32_e32 v10, v10, v0
	v_sub_f32_e32 v2, v2, v0
	v_mul_f32_e32 v10, v1, v10
	v_mul_f32_e32 v2, v1, v2
	v_fma_f32 v10, v54, v10, v112
	v_fma_f32 v2, v55, v2, v113
	v_cvt_pk_bf16_f32 v10, v10, s0
	v_cvt_pk_bf16_f32 v2, v2, s0
	ds_write_b16 v90, v10
	ds_write_b16 v91, v2 offset:272
	v_lshlrev_b32_e32 v2, 16, v149
	v_sub_f32_e32 v2, v2, v0
	v_and_b32_e32 v3, 0xffff0000, v149
	v_mul_f32_e32 v2, v1, v2
	v_sub_f32_e32 v3, v3, v0
	v_fma_f32 v2, v2, v56, v114
	v_mul_f32_e32 v3, v1, v3
	v_fmac_f32_e32 v115, v3, v57
	v_cvt_pk_bf16_f32 v2, v2, s0
	ds_write_b16 v92, v2
	v_cvt_pk_bf16_f32 v2, v115, s0
	ds_write_b16 v93, v2 offset:272
	v_lshlrev_b32_e32 v2, 16, v150
	v_sub_f32_e32 v2, v2, v0
	v_and_b32_e32 v3, 0xffff0000, v150
	v_mul_f32_e32 v2, v1, v2
	v_sub_f32_e32 v3, v3, v0
	v_fma_f32 v2, v2, v6, v108
	v_mul_f32_e32 v3, v1, v3
	v_fma_f32 v3, v3, v7, v109
	v_cvt_pk_bf16_f32 v2, v2, s0
	ds_write_b16 v94, v2
	v_cvt_pk_bf16_f32 v2, v3, s0
	ds_write_b16 v95, v2 offset:272
	v_lshlrev_b32_e32 v2, 16, v151
	v_sub_f32_e32 v2, v2, v0
	v_and_b32_e32 v3, 0xffff0000, v151
	v_mul_f32_e32 v2, v1, v2
	v_sub_f32_e32 v0, v3, v0
	v_fma_f32 v2, v2, v8, v110
	v_mul_f32_e32 v0, v1, v0
	v_fmac_f32_e32 v111, v0, v9
	v_cvt_pk_bf16_f32 v0, v2, s0
	ds_write_b16 v96, v0
	v_cvt_pk_bf16_f32 v0, v111, s0
	ds_write_b16 v97, v0 offset:272
	v_lshlrev_b64 v[0:1], 8, v[52:53]
	v_lshl_add_u64 v[0:1], v[12:13], 0, v[0:1]
	v_mov_b32_e32 v4, v150
	v_mov_b32_e32 v5, v151
	s_waitcnt lgkmcnt(0)
	s_barrier
	global_load_dwordx4 v[152:155], v[0:1], off
	global_load_dwordx4 v[156:159], v[0:1], off offset:64
	global_load_dwordx4 v[160:163], v[0:1], off offset:128
	global_load_dwordx4 v[164:167], v[0:1], off offset:192
	ds_read_b128 v[6:9], v98
	ds_read_b128 v[54:57], v98 offset:4352
	ds_read_b128 v[58:61], v98 offset:8704
	ds_read_b128 v[104:107], v98 offset:13056
	ds_read_b128 v[108:111], v98 offset:17408
	ds_read_b128 v[112:115], v98 offset:21760
	ds_read_b128 v[116:119], v98 offset:26112
	ds_read_b128 v[120:123], v98 offset:30464
	s_waitcnt vmcnt(3) lgkmcnt(0)
	v_mfma_f32_16x16x32_bf16 v[6:9], v[6:9], v[152:155], 0
	ds_read_b128 v[124:127], v98 offset:64
	v_mfma_f32_16x16x32_bf16 v[54:57], v[54:57], v[152:155], 0
	v_mfma_f32_16x16x32_bf16 v[58:61], v[58:61], v[152:155], 0
	v_mfma_f32_16x16x32_bf16 v[104:107], v[104:107], v[152:155], 0
	v_mfma_f32_16x16x32_bf16 v[108:111], v[108:111], v[152:155], 0
	v_mfma_f32_16x16x32_bf16 v[112:115], v[112:115], v[152:155], 0
	v_mfma_f32_16x16x32_bf16 v[116:119], v[116:119], v[152:155], 0
	v_mfma_f32_16x16x32_bf16 v[2:5], v[120:123], v[152:155], 0
	s_waitcnt vmcnt(2) lgkmcnt(0)
	v_mfma_f32_16x16x32_bf16 v[6:9], v[124:127], v[156:159], v[6:9]
	ds_read_b128 v[124:127], v98 offset:4416
	s_waitcnt lgkmcnt(0)
	v_mfma_f32_16x16x32_bf16 v[54:57], v[124:127], v[156:159], v[54:57]
	ds_read_b128 v[124:127], v98 offset:8768
	s_waitcnt lgkmcnt(0)
	v_mfma_f32_16x16x32_bf16 v[58:61], v[124:127], v[156:159], v[58:61]
	ds_read_b128 v[124:127], v98 offset:13120
	s_waitcnt lgkmcnt(0)
	v_mfma_f32_16x16x32_bf16 v[104:107], v[124:127], v[156:159], v[104:107]
	ds_read_b128 v[124:127], v98 offset:17472
	s_waitcnt lgkmcnt(0)
	v_mfma_f32_16x16x32_bf16 v[108:111], v[124:127], v[156:159], v[108:111]
	ds_read_b128 v[124:127], v98 offset:21824
	s_waitcnt lgkmcnt(0)
	v_mfma_f32_16x16x32_bf16 v[112:115], v[124:127], v[156:159], v[112:115]
	ds_read_b128 v[124:127], v98 offset:26176
	s_waitcnt lgkmcnt(0)
	v_mfma_f32_16x16x32_bf16 v[116:119], v[124:127], v[156:159], v[116:119]
	ds_read_b128 v[124:127], v98 offset:30528
	s_waitcnt lgkmcnt(0)
	v_mfma_f32_16x16x32_bf16 v[2:5], v[124:127], v[156:159], v[2:5]
	ds_read_b128 v[124:127], v98 offset:128
	s_waitcnt vmcnt(1) lgkmcnt(0)
	v_mfma_f32_16x16x32_bf16 v[6:9], v[124:127], v[160:163], v[6:9]
	ds_read_b128 v[124:127], v98 offset:4480
	s_waitcnt lgkmcnt(0)
	v_mfma_f32_16x16x32_bf16 v[54:57], v[124:127], v[160:163], v[54:57]
	ds_read_b128 v[124:127], v98 offset:8832
	s_waitcnt lgkmcnt(0)
	v_mfma_f32_16x16x32_bf16 v[58:61], v[124:127], v[160:163], v[58:61]
	ds_read_b128 v[124:127], v98 offset:13184
	s_waitcnt lgkmcnt(0)
	v_mfma_f32_16x16x32_bf16 v[104:107], v[124:127], v[160:163], v[104:107]
	ds_read_b128 v[124:127], v98 offset:17536
	s_waitcnt lgkmcnt(0)
	v_mfma_f32_16x16x32_bf16 v[108:111], v[124:127], v[160:163], v[108:111]
	ds_read_b128 v[124:127], v98 offset:21888
	s_waitcnt lgkmcnt(0)
	v_mfma_f32_16x16x32_bf16 v[112:115], v[124:127], v[160:163], v[112:115]
	ds_read_b128 v[124:127], v98 offset:26240
	s_waitcnt lgkmcnt(0)
	v_mfma_f32_16x16x32_bf16 v[116:119], v[124:127], v[160:163], v[116:119]
	ds_read_b128 v[124:127], v98 offset:30592
	s_waitcnt lgkmcnt(0)
	v_mfma_f32_16x16x32_bf16 v[2:5], v[124:127], v[160:163], v[2:5]
	ds_read_b128 v[124:127], v98 offset:192
	s_waitcnt vmcnt(0) lgkmcnt(0)
	v_mfma_f32_16x16x32_bf16 v[6:9], v[124:127], v[164:167], v[6:9]
	ds_read_b128 v[124:127], v98 offset:4544
	s_waitcnt lgkmcnt(0)
	v_mfma_f32_16x16x32_bf16 v[54:57], v[124:127], v[164:167], v[54:57]
	ds_read_b128 v[124:127], v98 offset:8896
	s_waitcnt lgkmcnt(0)
	v_mfma_f32_16x16x32_bf16 v[58:61], v[124:127], v[164:167], v[58:61]
	ds_read_b128 v[124:127], v98 offset:13248
	s_waitcnt lgkmcnt(0)
	v_mfma_f32_16x16x32_bf16 v[104:107], v[124:127], v[164:167], v[104:107]
	ds_read_b128 v[124:127], v98 offset:17600
	s_waitcnt lgkmcnt(0)
	v_mfma_f32_16x16x32_bf16 v[108:111], v[124:127], v[164:167], v[108:111]
	ds_read_b128 v[124:127], v98 offset:21952
	s_waitcnt lgkmcnt(0)
	v_mfma_f32_16x16x32_bf16 v[112:115], v[124:127], v[164:167], v[112:115]
	ds_read_b128 v[124:127], v98 offset:26304
	s_waitcnt lgkmcnt(0)
; #define MFMA16(a, b, c) __builtin_amdgcn_mfma_f32_16x16x32_bf16((a), (b), (c), 0, 0, 0)
;     ...
;       for (int ks = 0; ks < 4; ++ks) {
;         bf16x8 af = *(const bf16x8*)(wp + ks * 32);
; #pragma unroll
;         for (int ns = 0; ns < 8; ++ns) {
;           bf16x8 bfr = *(const bf16x8*)(vT + (ns * 16 + fr) * 136 + ks * 32 + fq * 8);
;           acc[ns] = MFMA16(bfr, af, acc[ns]);
;         }
;       }
;       {
;         const int tl = wid * 16 + fr;
;         const float bias = sb[g * 128 + tl];
;         float* mx = (float*)(shm + 36864);
; #pragma unroll
;         for (int ns = 0; ns < 8; ++ns) {
;           f32x4 v = acc[ns];
;           v[0] += bias; v[1] += bias; v[2] += bias; v[3] += bias;
;           *(f32x4*)(mx + tl * 132 + ns * 16 + fq * 4) = v;
;         }
;       }
	v_mfma_f32_16x16x32_bf16 v[116:119], v[124:127], v[164:167], v[116:119]
	ds_read_b128 v[124:127], v98 offset:30656
	s_waitcnt lgkmcnt(0)
	v_mfma_f32_16x16x32_bf16 v[0:3], v[124:127], v[164:167], v[2:5]
	v_mov_b32_e32 v120, v164
	v_mov_b32_e32 v121, v165
	v_mov_b32_e32 v122, v166
	v_mov_b32_e32 v123, v167
	s_nop 2
	v_lshl_add_u64 v[4:5], v[52:53], 2, s[14:15]
	global_load_dword v10, v[4:5], off
	v_add_u32_e32 v52, 0x80, v52
	s_waitcnt vmcnt(0)
	v_pk_add_f32 v[8:9], v[8:9], v[10:11] op_sel_hi:[1,0]
	v_pk_add_f32 v[6:7], v[6:7], v[10:11] op_sel_hi:[1,0]
	ds_write_b128 v99, v[6:9] offset:36864
	v_pk_add_f32 v[6:7], v[56:57], v[10:11] op_sel_hi:[1,0]
	v_pk_add_f32 v[4:5], v[54:55], v[10:11] op_sel_hi:[1,0]
	ds_write_b128 v99, v[4:7] offset:36928
	v_pk_add_f32 v[6:7], v[60:61], v[10:11] op_sel_hi:[1,0]
	v_pk_add_f32 v[4:5], v[58:59], v[10:11] op_sel_hi:[1,0]
	ds_write_b128 v99, v[4:7] offset:36992
	v_pk_add_f32 v[6:7], v[106:107], v[10:11] op_sel_hi:[1,0]
	v_pk_add_f32 v[4:5], v[104:105], v[10:11] op_sel_hi:[1,0]
	ds_write_b128 v99, v[4:7] offset:37056
	v_pk_add_f32 v[6:7], v[110:111], v[10:11] op_sel_hi:[1,0]
	v_pk_add_f32 v[4:5], v[108:109], v[10:11] op_sel_hi:[1,0]
	ds_write_b128 v99, v[4:7] offset:37120
	v_pk_add_f32 v[6:7], v[114:115], v[10:11] op_sel_hi:[1,0]
	v_pk_add_f32 v[4:5], v[112:113], v[10:11] op_sel_hi:[1,0]
	ds_write_b128 v99, v[4:7] offset:37184
	v_pk_add_f32 v[6:7], v[118:119], v[10:11] op_sel_hi:[1,0]
	v_pk_add_f32 v[4:5], v[116:117], v[10:11] op_sel_hi:[1,0]
	v_pk_add_f32 v[2:3], v[10:11], v[2:3] op_sel_hi:[0,1]
	v_pk_add_f32 v[0:1], v[10:11], v[0:1] op_sel_hi:[0,1]
	v_lshl_add_u64 v[8:9], s[18:19], 0, v[34:35]
	ds_write_b128 v99, v[4:7] offset:37248
	ds_write_b128 v99, v[0:3] offset:37312
	s_waitcnt lgkmcnt(0)
	s_barrier
; DI float bflo(unsigned v) { return __uint_as_float(v << 16); }
; DI float bfhi(unsigned v) { return __uint_as_float(v & 0xffff0000u); }
;     ...
;       {
;         const float* mx = (const float*)(shm + 36864);
; #pragma unroll
;         for (int i = 0; i < 4; ++i) {
;           const int chunk = tid + i * 512, tl = chunk >> 4, c8 = (chunk & 15) * 8, tt = T0 + tl;
;           const f32x4 m0 = *(const f32x4*)(mx + tl * 132 + c8), m1 = *(const f32x4*)(mx + tl * 132 + c8 + 4);
;           const i32x4 u = *(const i32x4*)(projA + (size_t)tt * 1024 + g * 128 + c8);
;           u16* d = actA + (size_t)tt * 512 + g * 128 + c8;
;           const i32x4 zg = *(const i32x4*)d;
;           i32x4 o;
;           o[0] = (int)pack2(bflo((unsigned)u[0]) * m0[0] * bflo((unsigned)zg[0]), bfhi((unsigned)u[0]) * m0[1] * bfhi((unsigned)zg[0]));
;           o[1] = (int)pack2(bflo((unsigned)u[1]) * m0[2] * bflo((unsigned)zg[1]), bfhi((unsigned)u[1]) * m0[3] * bfhi((unsigned)zg[1]));
;           o[2] = (int)pack2(bflo((unsigned)u[2]) * m1[0] * bflo((unsigned)zg[2]), bfhi((unsigned)u[2]) * m1[1] * bfhi((unsigned)zg[2]));
;           o[3] = (int)pack2(bflo((unsigned)u[3]) * m1[2] * bflo((unsigned)zg[3]), bfhi((unsigned)u[3]) * m1[3] * bfhi((unsigned)zg[3]));
;           if (!dry) *(i32x4*)d = o;
;         }
;       }
;       __syncthreads();
;     }
	ds_read_b128 v[4:7], v100 offset:36864
	ds_read_b128 v[0:3], v100 offset:36880
	global_load_dwordx4 v[8:11], v[8:9], off
	v_lshl_add_u64 v[58:59], s[18:19], 0, v[50:51]
	global_load_dwordx4 v[54:57], v[58:59], off
	s_waitcnt vmcnt(0) lgkmcnt(0)
	v_lshlrev_b32_e32 v60, 16, v8
	v_and_b32_e32 v61, 0xffff0000, v8
	v_lshlrev_b32_e32 v8, 16, v9
	v_and_b32_e32 v9, 0xffff0000, v9
	v_pk_mul_f32 v[4:5], v[4:5], v[60:61]
	v_lshlrev_b32_e32 v60, 16, v54
	v_and_b32_e32 v61, 0xffff0000, v54
	v_pk_mul_f32 v[6:7], v[6:7], v[8:9]
	v_lshlrev_b32_e32 v8, 16, v55
	v_and_b32_e32 v9, 0xffff0000, v55
	v_pk_mul_f32 v[4:5], v[4:5], v[60:61]
	v_pk_mul_f32 v[6:7], v[6:7], v[8:9]
	v_cvt_pk_bf16_f32 v4, v4, v5
	v_cvt_pk_bf16_f32 v5, v6, v7
	v_lshlrev_b32_e32 v6, 16, v10
	v_and_b32_e32 v7, 0xffff0000, v10
	v_pk_mul_f32 v[0:1], v[0:1], v[6:7]
	v_lshlrev_b32_e32 v6, 16, v56
	v_and_b32_e32 v7, 0xffff0000, v56
	v_pk_mul_f32 v[0:1], v[0:1], v[6:7]
	v_lshl_add_u64 v[8:9], s[18:19], 0, v[36:37]
	v_cvt_pk_bf16_f32 v6, v0, v1
	v_lshlrev_b32_e32 v0, 16, v11
	v_and_b32_e32 v1, 0xffff0000, v11
	v_pk_mul_f32 v[0:1], v[2:3], v[0:1]
	v_lshlrev_b32_e32 v2, 16, v57
	v_and_b32_e32 v3, 0xffff0000, v57
	v_pk_mul_f32 v[0:1], v[0:1], v[2:3]
	s_nop 0
	v_cvt_pk_bf16_f32 v7, v0, v1
	global_store_dwordx4 v[58:59], v[4:7], off
	ds_read_b128 v[0:3], v101 offset:36864
	ds_read_b128 v[4:7], v101 offset:36880
	global_load_dwordx4 v[8:11], v[8:9], off
	v_lshl_add_u64 v[58:59], s[18:19], 0, v[48:49]
	global_load_dwordx4 v[54:57], v[58:59], off
	s_waitcnt vmcnt(0) lgkmcnt(0)
	v_lshlrev_b32_e32 v60, 16, v8
	v_and_b32_e32 v61, 0xffff0000, v8
	v_lshlrev_b32_e32 v8, 16, v9
	v_and_b32_e32 v9, 0xffff0000, v9
	v_pk_mul_f32 v[0:1], v[0:1], v[60:61]
	v_lshlrev_b32_e32 v60, 16, v54
	v_and_b32_e32 v61, 0xffff0000, v54
	v_pk_mul_f32 v[2:3], v[2:3], v[8:9]
	v_lshlrev_b32_e32 v8, 16, v55
	v_and_b32_e32 v9, 0xffff0000, v55
	v_pk_mul_f32 v[0:1], v[0:1], v[60:61]
	v_pk_mul_f32 v[2:3], v[2:3], v[8:9]
	v_cvt_pk_bf16_f32 v0, v0, v1
	v_cvt_pk_bf16_f32 v1, v2, v3
	v_lshlrev_b32_e32 v2, 16, v10
	v_and_b32_e32 v3, 0xffff0000, v10
	v_pk_mul_f32 v[2:3], v[4:5], v[2:3]
	v_lshlrev_b32_e32 v4, 16, v56
	v_and_b32_e32 v5, 0xffff0000, v56
	v_pk_mul_f32 v[2:3], v[2:3], v[4:5]
	v_lshlrev_b32_e32 v4, 16, v11
	v_and_b32_e32 v5, 0xffff0000, v11
	v_pk_mul_f32 v[4:5], v[6:7], v[4:5]
	v_lshlrev_b32_e32 v6, 16, v57
	v_and_b32_e32 v7, 0xffff0000, v57
	v_pk_mul_f32 v[4:5], v[4:5], v[6:7]
	v_cvt_pk_bf16_f32 v2, v2, v3
	v_cvt_pk_bf16_f32 v3, v4, v5
	global_store_dwordx4 v[58:59], v[0:3], off
	v_lshl_add_u64 v[8:9], s[18:19], 0, v[38:39]
	ds_read_b128 v[4:7], v102 offset:36864
	ds_read_b128 v[0:3], v102 offset:36880
	global_load_dwordx4 v[8:11], v[8:9], off
	v_lshl_add_u64 v[58:59], s[18:19], 0, v[46:47]
	global_load_dwordx4 v[54:57], v[58:59], off
	s_waitcnt vmcnt(0) lgkmcnt(0)
	v_lshlrev_b32_e32 v60, 16, v8
	v_and_b32_e32 v61, 0xffff0000, v8
	v_lshlrev_b32_e32 v8, 16, v9
	v_and_b32_e32 v9, 0xffff0000, v9
	v_pk_mul_f32 v[4:5], v[4:5], v[60:61]
	v_lshlrev_b32_e32 v60, 16, v54
	v_and_b32_e32 v61, 0xffff0000, v54
	v_pk_mul_f32 v[6:7], v[6:7], v[8:9]
	v_lshlrev_b32_e32 v8, 16, v55
	v_and_b32_e32 v9, 0xffff0000, v55
	v_pk_mul_f32 v[4:5], v[4:5], v[60:61]
	v_pk_mul_f32 v[6:7], v[6:7], v[8:9]
	v_cvt_pk_bf16_f32 v4, v4, v5
	v_cvt_pk_bf16_f32 v5, v6, v7
	v_lshlrev_b32_e32 v6, 16, v10
	v_and_b32_e32 v7, 0xffff0000, v10
	v_pk_mul_f32 v[0:1], v[0:1], v[6:7]
	v_lshlrev_b32_e32 v6, 16, v56
	v_and_b32_e32 v7, 0xffff0000, v56
	v_pk_mul_f32 v[0:1], v[0:1], v[6:7]
	v_lshl_add_u64 v[8:9], s[18:19], 0, v[40:41]
	v_cvt_pk_bf16_f32 v6, v0, v1
	v_lshlrev_b32_e32 v0, 16, v11
	v_and_b32_e32 v1, 0xffff0000, v11
	v_pk_mul_f32 v[0:1], v[2:3], v[0:1]
	v_lshlrev_b32_e32 v2, 16, v57
	v_and_b32_e32 v3, 0xffff0000, v57
	v_pk_mul_f32 v[0:1], v[0:1], v[2:3]
	s_nop 0
	v_cvt_pk_bf16_f32 v7, v0, v1
	global_store_dwordx4 v[58:59], v[4:7], off
	ds_read_b128 v[4:7], v103 offset:36864
	ds_read_b128 v[0:3], v103 offset:36880
	global_load_dwordx4 v[8:11], v[8:9], off
	v_lshl_add_u64 v[58:59], s[18:19], 0, v[44:45]
	global_load_dwordx4 v[54:57], v[58:59], off
	s_add_u32 s18, s18, 0x100
	s_addc_u32 s19, s19, 0
	s_cmpk_eq_i32 s16, 0x800
	s_waitcnt vmcnt(0) lgkmcnt(0)
	v_lshlrev_b32_e32 v60, 16, v8
	v_and_b32_e32 v61, 0xffff0000, v8
	v_lshlrev_b32_e32 v8, 16, v9
	v_and_b32_e32 v9, 0xffff0000, v9
	v_pk_mul_f32 v[4:5], v[4:5], v[60:61]
	v_lshlrev_b32_e32 v60, 16, v54
	v_and_b32_e32 v61, 0xffff0000, v54
	v_pk_mul_f32 v[6:7], v[6:7], v[8:9]
	v_lshlrev_b32_e32 v8, 16, v55
	v_and_b32_e32 v9, 0xffff0000, v55
	v_pk_mul_f32 v[4:5], v[4:5], v[60:61]
	v_pk_mul_f32 v[6:7], v[6:7], v[8:9]
	v_cvt_pk_bf16_f32 v4, v4, v5
	v_cvt_pk_bf16_f32 v5, v6, v7
	v_lshlrev_b32_e32 v6, 16, v10
	v_and_b32_e32 v7, 0xffff0000, v10
	v_pk_mul_f32 v[0:1], v[0:1], v[6:7]
	v_lshlrev_b32_e32 v6, 16, v56
	v_and_b32_e32 v7, 0xffff0000, v56
	v_pk_mul_f32 v[0:1], v[0:1], v[6:7]
	s_nop 0
	v_cvt_pk_bf16_f32 v6, v0, v1
	v_lshlrev_b32_e32 v0, 16, v11
	v_and_b32_e32 v1, 0xffff0000, v11
	v_pk_mul_f32 v[0:1], v[2:3], v[0:1]
	v_lshlrev_b32_e32 v2, 16, v57
	v_and_b32_e32 v3, 0xffff0000, v57
	v_pk_mul_f32 v[0:1], v[0:1], v[2:3]
	s_nop 0
	v_cvt_pk_bf16_f32 v7, v0, v1
	global_store_dwordx4 v[58:59], v[4:7], off
	s_waitcnt lgkmcnt(0)
	s_barrier
	s_cbranch_scc0 .LBB0_781
	s_add_i32 s4, s4, s72
	v_add_u32_e32 v16, s81, v16
	v_add_u32_e32 v18, s81, v18
	v_add_u32_e32 v20, s81, v20
	v_add_u32_e32 v22, s81, v22
	s_cmpk_gt_i32 s4, 0xff
	v_add_u32_e32 v30, s81, v30
	s_cbranch_scc0 .LBB0_778
	v_readlane_b32 s8, v253, 2
	v_readlane_b32 s50, v252, 18
	v_readlane_b32 s9, v253, 3
	v_readlane_b32 s51, v252, 19
	s_movk_i32 s42, 0xfc0
	v_readlane_b32 s46, v252, 31
	s_mov_b64 s[34:35], 0x20000
	s_mov_b64 s[36:37], 0x8000
	s_mov_b64 s[38:39], 0x18000
	v_readlane_b32 s10, v253, 4
	v_readlane_b32 s11, v253, 5
	v_readlane_b32 s12, v253, 6
	v_readlane_b32 s13, v253, 7
	v_readlane_b32 s14, v253, 8
	v_readlane_b32 s15, v253, 9
	v_readlane_b32 s16, v253, 10
	v_readlane_b32 s17, v253, 11
	v_readlane_b32 s18, v253, 12
	v_readlane_b32 s19, v253, 13
	v_readlane_b32 s20, v253, 14
	v_readlane_b32 s21, v253, 15
	v_readlane_b32 s22, v253, 16
	v_readlane_b32 s23, v253, 17

; DI int tid_() { int t = threadIdx.x; asm volatile("" : "+v"(t)); return t; }
; DI void phase_norm(const float* xin, u16* hb) {
;   const int lane = tid_() & 63, gw = blockIdx.x * 8 + (tid_() >> 6), nw = gridDim.x * 8;
;   for (int t = gw; t < T_TOK; t += nw) {
;     const float* r = xin + (size_t)t * DM;
;     float4 v[4];
;     float ss = 0.f;
; #pragma unroll
;     for (int i = 0; i < 4; ++i) {
;       v[i] = *(const float4*)(r + i * 256 + lane * 4);
;       ss += v[i].x * v[i].x + v[i].y * v[i].y + v[i].z * v[i].z + v[i].w * v[i].w;
;     }
; #pragma unroll
;     for (int o = 32; o > 0; o >>= 1) ss += __shfl_xor(ss, o);
;     const float rs = rsqrtf(ss * (1.f / DM) + EPS);
; #pragma unroll
;     for (int i = 0; i < 4; ++i) {
;       u32x2 o = {pack2(v[i].x * rs, v[i].y * rs), pack2(v[i].z * rs, v[i].w * rs)};
;       *(u32x2*)(hb + (size_t)t * DM + i * 256 + lane * 4) = o;
;     }
;   }
.Lnrm_b:
	v_mov_b32_e32 v6, v40
	v_mov_b32_e32 v7, v41
	v_mov_b32_e32 v8, v42
	v_mov_b32_e32 v9, v43
	v_mov_b32_e32 v10, v44
	v_mov_b32_e32 v11, v45
	v_mov_b32_e32 v12, v46
	v_mov_b32_e32 v13, v47
	v_add_u32_e32 v0, s84, v0
	v_mov_b32_e32 v20, v7
	v_mov_b32_e32 v21, v11
	v_mov_b32_e32 v18, v6
	v_mov_b32_e32 v19, v10
	v_pk_mul_f32 v[20:21], v[20:21], v[20:21]
	v_mov_b32_e32 v14, v8
	v_mov_b32_e32 v15, v12
	v_pk_fma_f32 v[18:19], v[18:19], v[18:19], v[20:21]
	v_mov_b32_e32 v16, v9
	v_mov_b32_e32 v17, v13
	v_pk_fma_f32 v[14:15], v[14:15], v[14:15], v[18:19]
	s_nop 0
	v_pk_fma_f32 v[22:23], v[16:17], v[16:17], v[14:15]
	v_mov_b32_e32 v14, v48
	v_mov_b32_e32 v15, v49
	v_mov_b32_e32 v16, v50
	v_mov_b32_e32 v17, v51
	v_mov_b32_e32 v18, v52
	v_mov_b32_e32 v19, v53
	v_mov_b32_e32 v20, v54
	v_mov_b32_e32 v21, v55
	v_add_f32_e32 v1, v22, v23
	v_lshl_add_u64 v[4:5], v[4:5], 0, s[12:13]
	v_cmp_lt_i32_e32 vcc, s60, v0
	s_cbranch_vccnz .Lnrm_skip_b
	global_load_dwordx4 v[40:43], v[4:5], off
	global_load_dwordx4 v[44:47], v[4:5], off offset:1024
	global_load_dwordx4 v[48:51], v[4:5], off offset:2048
	global_load_dwordx4 v[52:55], v[4:5], off offset:3072
.Lnrm_skip_b:
	v_mov_b32_e32 v30, v15
	v_mov_b32_e32 v31, v19
	v_mov_b32_e32 v28, v14
	v_mov_b32_e32 v29, v18
	v_pk_mul_f32 v[30:31], v[30:31], v[30:31]
	v_mov_b32_e32 v24, v16
	v_mov_b32_e32 v25, v20
	v_pk_fma_f32 v[28:29], v[28:29], v[28:29], v[30:31]
	v_mov_b32_e32 v26, v17
	v_mov_b32_e32 v27, v21
	v_pk_fma_f32 v[24:25], v[24:25], v[24:25], v[28:29]
	s_nop 0
	v_pk_fma_f32 v[24:25], v[26:27], v[26:27], v[24:25]
	s_nop 0
	v_add_f32_e32 v1, v1, v24
	v_add_f32_e32 v1, v1, v25
	ds_bpermute_b32 v22, v211, v1
	s_waitcnt lgkmcnt(0)
	v_add_f32_e32 v1, v1, v22
	ds_bpermute_b32 v22, v212, v1
	s_waitcnt lgkmcnt(0)
	v_add_f32_e32 v1, v1, v22
	ds_bpermute_b32 v22, v213, v1
	s_waitcnt lgkmcnt(0)
	v_add_f32_e32 v1, v1, v22
	ds_bpermute_b32 v22, v214, v1
	s_waitcnt lgkmcnt(0)
	v_add_f32_e32 v1, v1, v22
	ds_bpermute_b32 v22, v215, v1
	s_waitcnt lgkmcnt(0)
	v_add_f32_e32 v1, v1, v22
	ds_bpermute_b32 v22, v216, v1
	s_waitcnt lgkmcnt(0)
	v_add_f32_e32 v1, v1, v22
	v_fmamk_f32 v1, v1, 0x3a800000, v134
	v_cmp_gt_f32_e32 vcc, s33, v1
	v_mul_f32_e32 v22, 0x4b800000, v1
	s_nop 0
	v_cndmask_b32_e32 v1, v1, v22, vcc
	v_rsq_f32_e32 v1, v1
	s_nop 0
	v_mul_f32_e32 v22, 0x45800000, v1
	v_cndmask_b32_e32 v22, v1, v22, vcc
	v_pk_mul_f32 v[6:7], v[6:7], v[22:23] op_sel_hi:[1,0]
	v_pk_mul_f32 v[8:9], v[8:9], v[22:23] op_sel_hi:[1,0]
	v_cvt_pk_bf16_f32 v6, v6, v7
	v_cvt_pk_bf16_f32 v7, v8, v9
	global_store_dwordx2 v[2:3], v[6:7], off
	v_pk_mul_f32 v[6:7], v[10:11], v[22:23] op_sel_hi:[1,0]
	v_pk_mul_f32 v[8:9], v[12:13], v[22:23] op_sel_hi:[1,0]
	v_cvt_pk_bf16_f32 v6, v6, v7
	v_cvt_pk_bf16_f32 v7, v8, v9
	global_store_dwordx2 v[2:3], v[6:7], off offset:512
	v_pk_mul_f32 v[6:7], v[14:15], v[22:23] op_sel_hi:[1,0]
	v_pk_mul_f32 v[8:9], v[16:17], v[22:23] op_sel_hi:[1,0]
	v_cvt_pk_bf16_f32 v6, v6, v7
	v_cvt_pk_bf16_f32 v7, v8, v9
	global_store_dwordx2 v[2:3], v[6:7], off offset:1024
	v_pk_mul_f32 v[6:7], v[18:19], v[22:23] op_sel_hi:[1,0]
	v_pk_mul_f32 v[8:9], v[20:21], v[22:23] op_sel_hi:[1,0]
	v_cvt_pk_bf16_f32 v6, v6, v7
	v_cvt_pk_bf16_f32 v7, v8, v9
	v_cmp_lt_i32_e32 vcc, s60, v0
	global_store_dwordx2 v[2:3], v[6:7], off offset:1536
	v_lshl_add_u64 v[2:3], v[2:3], 0, s[10:11]
	s_or_b64 s[4:5], vcc, s[4:5]
	s_andn2_b64 exec, exec, s[4:5]
	s_waitcnt vmcnt(4)
	s_cbranch_execnz .Lnrm_b
